# instruction selection: v_pk_mul_f32 with broadcast operand (rstd / decay scaling) replaced by two v_mul_f32; plus loop-edge and peeled-step wait edits
# speedup vs baseline: 1.0036x; 1.0036x over previous
; template <bool IN_PROJ>
; DI void gemm_tile(const Params& p, int layer, int nt, int tt, char* smem) {
;     ...
; #pragma unroll
;   for (int ti = 0; ti < 2; ++ti) {
;     const int t = t0 + wt * 64 + ti * 32 + r;
;     const float rs = rstd[t];
; #pragma unroll
;     for (int fi = 0; fi < 4; ++fi)
; #pragma unroll
;       for (int i = 0; i < 16; ++i) acc[fi][ti][i] *= rs;
;     if (d.kind == K_SILU) {
.LBB0_89:
	s_xor_b64 s[4:5], s[0:1], -1
	v_or_b32_e32 v96, s92, v192
	v_readlane_b32 s0, v249, 10
	v_ashrrev_i32_e32 v97, 31, v96
	v_readlane_b32 s1, v249, 11
	s_xor_b64 s[8:9], s[2:3], -1
	s_mov_b64 s[64:65], -1
	v_lshl_add_u64 v[194:195], v[96:97], 2, s[0:1]
	v_mov_b32_e32 v160, v204
	s_mov_b64 s[10:11], 0
	s_cmp_lt_i32 s73, 2
	s_mov_b64 s[2:3], 0
	s_mov_b64 s[0:1], 0
	s_mov_b64 s[60:61], 0
	s_waitcnt vmcnt(0)
	v_mul_f32_e32 v128, v64, v160
	v_mul_f32_e32 v129, v65, v160
	v_mul_f32_e32 v130, v66, v160
	v_mul_f32_e32 v131, v67, v160
	v_mul_f32_e32 v132, v68, v160
	v_mul_f32_e32 v133, v69, v160
	v_mul_f32_e32 v134, v70, v160
	v_mul_f32_e32 v135, v71, v160
	v_mul_f32_e32 v136, v72, v160
	v_mul_f32_e32 v137, v73, v160
	v_mul_f32_e32 v138, v74, v160
	v_mul_f32_e32 v139, v75, v160
	v_mul_f32_e32 v140, v76, v160
	v_mul_f32_e32 v141, v77, v160
	v_mul_f32_e32 v142, v78, v160
	v_mul_f32_e32 v143, v79, v160
	v_mul_f32_e32 v96, v80, v160
	v_mul_f32_e32 v97, v81, v160
	v_mul_f32_e32 v98, v82, v160
	v_mul_f32_e32 v99, v83, v160
	v_mul_f32_e32 v100, v84, v160
	v_mul_f32_e32 v101, v85, v160
	v_mul_f32_e32 v102, v86, v160
	v_mul_f32_e32 v103, v87, v160
	v_mul_f32_e32 v104, v88, v160
	v_mul_f32_e32 v105, v89, v160
	v_mul_f32_e32 v106, v90, v160
	v_mul_f32_e32 v107, v91, v160
	v_mul_f32_e32 v108, v92, v160
	v_mul_f32_e32 v109, v93, v160
	v_mul_f32_e32 v110, v94, v160
	v_mul_f32_e32 v111, v95, v160
	v_mul_f32_e32 v80, v112, v160
	v_mul_f32_e32 v81, v113, v160
	v_mul_f32_e32 v82, v114, v160
	v_mul_f32_e32 v83, v115, v160
	v_mul_f32_e32 v84, v116, v160
	v_mul_f32_e32 v85, v117, v160
	v_mul_f32_e32 v86, v118, v160
	v_mul_f32_e32 v87, v119, v160
	v_mul_f32_e32 v88, v120, v160
	v_mul_f32_e32 v89, v121, v160
	v_mul_f32_e32 v90, v122, v160
	v_mul_f32_e32 v91, v123, v160
	v_mul_f32_e32 v92, v124, v160
	v_mul_f32_e32 v93, v125, v160
	v_mul_f32_e32 v94, v126, v160
	v_mul_f32_e32 v95, v127, v160
	v_mul_f32_e32 v64, v144, v160
	v_mul_f32_e32 v65, v145, v160
	v_mul_f32_e32 v66, v146, v160
	v_mul_f32_e32 v67, v147, v160
	v_mul_f32_e32 v68, v148, v160
	v_mul_f32_e32 v69, v149, v160
	v_mul_f32_e32 v70, v150, v160
	v_mul_f32_e32 v71, v151, v160
	v_mul_f32_e32 v72, v152, v160
	v_mul_f32_e32 v73, v153, v160
	v_mul_f32_e32 v74, v154, v160
	v_mul_f32_e32 v75, v155, v160
	v_mul_f32_e32 v76, v156, v160
	v_mul_f32_e32 v77, v157, v160
	v_mul_f32_e32 v78, v158, v160
	v_mul_f32_e32 v79, v159, v160
	s_cbranch_scc1 .LBB0_101
	s_cmp_gt_i32 s73, 4
	s_cbranch_scc0 .LBB0_93
	s_mov_b64 s[60:61], -1
	s_mov_b64 s[64:65], 0
	s_cmp_eq_u32 s73, 5
	s_cbranch_scc0 .LBB0_93
	s_mov_b64 s[60:61], 0
	s_mov_b64 s[2:3], -1

; template <bool IN_PROJ>
; DI void gemm_tile(const Params& p, int layer, int nt, int tt, char* smem) {
;     ...
; #pragma unroll
;   for (int ti = 0; ti < 2; ++ti) {
;     const int t = t0 + wt * 64 + ti * 32 + r;
;     const float rs = rstd[t];
; #pragma unroll
;     for (int fi = 0; fi < 4; ++fi)
; #pragma unroll
;       for (int i = 0; i < 16; ++i) acc[fi][ti][i] *= rs;
;     if (d.kind == K_SILU) {
.LBB0_173:
	v_mov_b32_e32 v96, v205
	s_mov_b64 s[64:65], -1
	s_mov_b64 s[10:11], 0
	s_cmp_lt_i32 s73, 2
	s_mov_b64 s[2:3], 0
	s_mov_b64 s[0:1], 0
	s_mov_b64 s[60:61], 0
	s_waitcnt vmcnt(0)
	v_mul_f32_e32 v80, v0, v96
	v_mul_f32_e32 v81, v1, v96
	v_mul_f32_e32 v82, v2, v96
	v_mul_f32_e32 v83, v3, v96
	v_mul_f32_e32 v84, v4, v96
	v_mul_f32_e32 v85, v5, v96
	v_mul_f32_e32 v86, v6, v96
	v_mul_f32_e32 v87, v7, v96
	v_mul_f32_e32 v88, v8, v96
	v_mul_f32_e32 v89, v9, v96
	v_mul_f32_e32 v90, v10, v96
	v_mul_f32_e32 v91, v11, v96
	v_mul_f32_e32 v92, v12, v96
	v_mul_f32_e32 v93, v13, v96
	v_mul_f32_e32 v94, v14, v96
	v_mul_f32_e32 v95, v15, v96
	v_mul_f32_e32 v64, v16, v96
	v_mul_f32_e32 v65, v17, v96
	v_mul_f32_e32 v66, v18, v96
	v_mul_f32_e32 v67, v19, v96
	v_mul_f32_e32 v68, v20, v96
	v_mul_f32_e32 v69, v21, v96
	v_mul_f32_e32 v70, v22, v96
	v_mul_f32_e32 v71, v23, v96
	v_mul_f32_e32 v72, v24, v96
	v_mul_f32_e32 v73, v25, v96
	v_mul_f32_e32 v74, v26, v96
	v_mul_f32_e32 v75, v27, v96
	v_mul_f32_e32 v76, v28, v96
	v_mul_f32_e32 v77, v29, v96
	v_mul_f32_e32 v78, v30, v96
	v_mul_f32_e32 v79, v31, v96
	v_mul_f32_e32 v16, v32, v96
	v_mul_f32_e32 v17, v33, v96
	v_mul_f32_e32 v18, v34, v96
	v_mul_f32_e32 v19, v35, v96
	v_mul_f32_e32 v20, v36, v96
	v_mul_f32_e32 v21, v37, v96
	v_mul_f32_e32 v22, v38, v96
	v_mul_f32_e32 v23, v39, v96
	v_mul_f32_e32 v24, v40, v96
	v_mul_f32_e32 v25, v41, v96
	v_mul_f32_e32 v26, v42, v96
	v_mul_f32_e32 v27, v43, v96
	v_mul_f32_e32 v28, v44, v96
	v_mul_f32_e32 v29, v45, v96
	v_mul_f32_e32 v30, v46, v96
	v_mul_f32_e32 v31, v47, v96
	v_mul_f32_e32 v0, v48, v96
	v_mul_f32_e32 v1, v49, v96
	v_mul_f32_e32 v2, v50, v96
	v_mul_f32_e32 v3, v51, v96
	v_mul_f32_e32 v4, v52, v96
	v_mul_f32_e32 v5, v53, v96
	v_mul_f32_e32 v6, v54, v96
	v_mul_f32_e32 v7, v55, v96
	v_mul_f32_e32 v8, v56, v96
	v_mul_f32_e32 v9, v57, v96
	v_mul_f32_e32 v10, v58, v96
	v_mul_f32_e32 v11, v59, v96
	v_mul_f32_e32 v12, v60, v96
	v_mul_f32_e32 v13, v61, v96
	v_mul_f32_e32 v14, v62, v96
	v_mul_f32_e32 v15, v63, v96
	s_cbranch_scc1 .LBB0_189
	s_cmp_gt_i32 s73, 4
	s_cbranch_scc0 .LBB0_177
	s_mov_b64 s[60:61], -1
	s_mov_b64 s[64:65], 0
	s_cmp_eq_u32 s73, 5
	s_cbranch_scc0 .LBB0_177
	s_mov_b64 s[60:61], 0
	s_mov_b64 s[2:3], -1

; DI u16 f2bf(float x) { return (u16)(pack2bf(x, 0.f) & 0xffffu); }
; DI float bf2f(u16 b) { return __uint_as_float(((u32)b) << 16); }
; DI float h2f(u16 b) { return (float)__builtin_bit_cast(_Float16, b); }
; template <int PASS>
; DI void hgrn_unit(const Params& p, int layer, int unit, char* smem) {
;     ...
; #pragma unroll
;     for (int j = 0; j < 32; ++j) {
;       float g = h2f(rG[j * 64 + lane]);
;       if (j < 16) tot0 += g; else tot1 += g;
;       if (j == 16) g16 = g;
;       if ((j >> 4) == half) gval[j & 15] = g;
;     }
; #pragma unroll
;     for (int jj = 0; jj < 16; ++jj) { if (PASS == 2) qraw[jj] = rQ[jj * 64 + lane]; vraw[jj] = rV[jj * 64 + lane]; }
;     asm volatile("s_waitcnt lgkmcnt(0)" ::: "memory");
;     __builtin_amdgcn_sched_barrier(0);
;     if (c + 1 < c_end) gl(c + 1);
;     __syncthreads();
;     const float bmid = tot0 + g16, blast = tot0 + tot1;
;     logD += blast;
;     float run = half ? tot0 : 0.f;
;     u32 klp[8], vtp[8];
;     if (PASS == 2) {
;       const float Emid = __expf(bmid), Elm = __expf(blast - bmid);
; #pragma unroll
;       for (int jj = 0; jj < 16; jj += 2) {
;         float kl2[2];
; #pragma unroll
;         for (int u = 0; u < 2; ++u) {
;           const int j = half * 16 + jj + u;
;           run += gval[jj + u];
;           float e1 = __expf(run - bmid), e2 = __expf(bmid - run);
;           float q = bf2f(qraw[jj + u]);
;           float k = 1.f - __expf(gval[jj + u]);
;           float qm = q * e1, km = k * e2;
;           kl2[u] = km * Elm;
;           sQm[j * HS + d] = f2bf(qm); sKm[j * HS + d] = f2bf(km); sQb[j * HS + d] = f2bf(qm * Emid);
.LBB0_606:
	s_waitcnt lgkmcnt(0)
	v_cvt_f32_f16_e32 v168, v168
	v_cvt_f32_f16_e32 v167, v167
	v_cvt_f32_f16_e32 v166, v166
	v_cvt_f32_f16_e32 v165, v165
	v_add_f32_e32 v169, 0, v168
	v_cvt_f32_f16_e32 v164, v164
	v_cndmask_b32_e64 v121, v121, v168, s[42:43]
	v_add_f32_e32 v168, v169, v167
	v_cvt_f32_f16_e32 v163, v163
	v_cndmask_b32_e64 v122, v122, v167, s[42:43]
	v_add_f32_e32 v167, v168, v166
	v_cvt_f32_f16_e32 v162, v162
	v_cndmask_b32_e64 v123, v123, v166, s[42:43]
	v_add_f32_e32 v166, v167, v165
	v_cvt_f32_f16_e32 v161, v161
	v_cndmask_b32_e64 v124, v124, v165, s[42:43]
	v_add_f32_e32 v165, v166, v164
	v_cvt_f32_f16_e32 v160, v160
	v_cndmask_b32_e64 v125, v125, v164, s[42:43]
	v_add_f32_e32 v164, v165, v163
	v_cvt_f32_f16_e32 v159, v159
	v_cndmask_b32_e64 v126, v126, v163, s[42:43]
	v_add_f32_e32 v163, v164, v162
	v_cvt_f32_f16_e32 v158, v158
	v_cndmask_b32_e64 v127, v127, v162, s[42:43]
	v_add_f32_e32 v162, v163, v161
	v_cvt_f32_f16_e32 v157, v157
	v_cndmask_b32_e64 v128, v128, v161, s[42:43]
	v_add_f32_e32 v161, v162, v160
	v_cvt_f32_f16_e32 v156, v156
	v_cndmask_b32_e64 v129, v129, v160, s[42:43]
	v_add_f32_e32 v160, v161, v159
	v_cvt_f32_f16_e32 v155, v155
	v_cndmask_b32_e64 v130, v130, v159, s[42:43]
	v_add_f32_e32 v159, v160, v158
	v_cndmask_b32_e64 v131, v131, v158, s[42:43]
	v_add_f32_e32 v158, v159, v157
	v_cndmask_b32_e64 v132, v132, v157, s[42:43]
	v_add_f32_e32 v157, v158, v156
	v_cndmask_b32_e64 v133, v133, v156, s[42:43]
	v_add_f32_e32 v156, v157, v155
	v_cndmask_b32_e64 v136, v136, v155, s[42:43]
	v_cvt_f32_f16_e32 v155, v153
	v_cvt_f32_f16_e32 v153, v152
	v_cvt_f32_f16_e32 v151, v151
	v_cvt_f32_f16_e32 v150, v150
	v_cvt_f32_f16_e32 v149, v149
	v_add_f32_e32 v152, 0, v153
	v_cvt_f32_f16_e32 v148, v148
	v_add_f32_e32 v152, v152, v151
	v_cvt_f32_f16_e32 v147, v147
	v_cndmask_b32_e64 v122, v122, v151, s[6:7]
	v_add_f32_e32 v151, v152, v150
	v_cvt_f32_f16_e32 v146, v146
	v_cndmask_b32_e64 v123, v123, v150, s[6:7]
	v_add_f32_e32 v150, v151, v149
	v_cvt_f32_f16_e32 v145, v145
	v_cndmask_b32_e64 v124, v124, v149, s[6:7]
	v_add_f32_e32 v149, v150, v148
	v_cvt_f32_f16_e32 v144, v144
	v_cndmask_b32_e64 v125, v125, v148, s[6:7]
	v_add_f32_e32 v148, v149, v147
	v_cvt_f32_f16_e32 v94, v94
	v_cndmask_b32_e64 v126, v126, v147, s[6:7]
	v_add_f32_e32 v147, v148, v146
	v_cvt_f32_f16_e32 v93, v93
	v_cndmask_b32_e64 v127, v127, v146, s[6:7]
	v_add_f32_e32 v146, v147, v145
	v_cvt_f32_f16_e32 v92, v92
	v_cndmask_b32_e64 v128, v128, v145, s[6:7]
	v_add_f32_e32 v145, v146, v144
	v_cvt_f32_f16_e32 v71, v71
	v_cndmask_b32_e64 v129, v129, v144, s[6:7]
	v_add_f32_e32 v144, v145, v94
	v_cvt_f32_f16_e32 v66, v66
	v_cvt_f32_f16_e32 v154, v154
	v_cndmask_b32_e64 v130, v130, v94, s[6:7]
	v_add_f32_e32 v94, v144, v93
	v_cvt_f32_f16_e32 v65, v65
	v_cndmask_b32_e64 v131, v131, v93, s[6:7]
	v_add_f32_e32 v93, v94, v92
	v_cvt_f32_f16_e32 v64, v64
	v_cndmask_b32_e64 v132, v132, v92, s[6:7]
	v_add_f32_e32 v92, v93, v71
	v_cndmask_b32_e64 v133, v133, v71, s[6:7]
	v_add_f32_e32 v71, v92, v66
	v_add_f32_e32 v156, v156, v154
	v_cndmask_b32_e64 v134, v134, v155, s[42:43]
	v_cndmask_b32_e64 v136, v136, v66, s[6:7]
	v_add_f32_e32 v66, v71, v65
	v_cndmask_b32_e64 v135, v135, v154, s[42:43]
	v_add_f32_e32 v154, v156, v155
	v_add_f32_e32 v152, v66, v64
	v_cndmask_b32_e64 v134, v134, v64, s[6:7]
	v_lshlrev_b32_e32 v64, 16, v76
	v_cndmask_b32_e64 v121, v121, v153, s[6:7]
	v_or_b32_sdwa v64, v64, v67 dst_sel:DWORD dst_unused:UNUSED_PAD src0_sel:DWORD src1_sel:WORD_0
	v_lshlrev_b32_e32 v67, 16, v91
	v_cndmask_b32_e64 v91, v154, 0, s[42:43]
	v_cndmask_b32_e64 v135, v135, v65, s[6:7]
	v_lshlrev_b32_e32 v65, 16, v77
	v_pk_add_f32 v[76:77], v[154:155], v[152:153] op_sel_hi:[0,1]
	v_add_f32_e32 v91, v91, v121
	v_sub_f32_e32 v92, v91, v77
	v_mul_f32_e32 v92, 0x3fb8aa3b, v92
	v_exp_f32_e32 v93, v92
	v_or_b32_sdwa v65, v65, v68 dst_sel:DWORD dst_unused:UNUSED_PAD src0_sel:DWORD src1_sel:WORD_0
	v_lshlrev_b32_e32 v68, 16, v140
	v_lshlrev_b32_e32 v66, 16, v78
	v_or_b32_sdwa v68, v68, v95 dst_sel:DWORD dst_unused:UNUSED_PAD src0_sel:DWORD src1_sel:WORD_0
	v_mul_f32_e32 v78, 0x3fb8aa3b, v77
	v_lshlrev_b32_e32 v95, 16, v90
	v_exp_f32_e32 v94, v78
	v_mul_f32_e32 v93, v93, v95
	v_cvt_pk_bf16_f32 v95, v93, s0
	s_nop 0
	s_barrier
; DI u32 pack2bf(float lo, float hi) { f32x2 v = {lo, hi}; return __builtin_bit_cast(u32, __builtin_convertvector(v, bf2_t)); }
; DI u16 f2bf(float x) { return (u16)(pack2bf(x, 0.f) & 0xffffu); }
; DI float bf2f(u16 b) { return __uint_as_float(((u32)b) << 16); }
; template <int PASS>
; DI void hgrn_unit(const Params& p, int layer, int unit, char* smem) {
;     ...
;       const float Emid = __expf(bmid), Elm = __expf(blast - bmid);
; #pragma unroll
;       for (int jj = 0; jj < 16; jj += 2) {
;         float kl2[2];
; #pragma unroll
;         for (int u = 0; u < 2; ++u) {
;           const int j = half * 16 + jj + u;
;           run += gval[jj + u];
;           float e1 = __expf(run - bmid), e2 = __expf(bmid - run);
;           float q = bf2f(qraw[jj + u]);
;           float k = 1.f - __expf(gval[jj + u]);
;           float qm = q * e1, km = k * e2;
;           kl2[u] = km * Elm;
;           sQm[j * HS + d] = f2bf(qm); sKm[j * HS + d] = f2bf(km); sQb[j * HS + d] = f2bf(qm * Emid);
;         }
;         klp[jj >> 1] = pack2bf(kl2[0], kl2[1]);
;       }
	ds_write_b16 v117, v95
	v_add_f32_e32 v95, v91, v122
	v_sub_f32_e32 v92, v77, v91
	v_sub_f32_e32 v91, v95, v77
	v_or_b32_sdwa v66, v66, v69 dst_sel:DWORD dst_unused:UNUSED_PAD src0_sel:DWORD src1_sel:WORD_0
	v_lshlrev_b32_e32 v69, 16, v141
	v_mul_f32_e32 v93, v94, v93
	v_mul_f32_e32 v91, 0x3fb8aa3b, v91
	v_or_b32_sdwa v69, v69, v137 dst_sel:DWORD dst_unused:UNUSED_PAD src0_sel:DWORD src1_sel:WORD_0
	v_cvt_pk_bf16_f32 v93, v93, s0
	v_exp_f32_e32 v137, v91
	v_sub_f32_e32 v91, v77, v95
	v_mul_f32_e32 v90, 0x3fb8aa3b, v121
	ds_write_b16 v117, v93 offset:17408
	v_mul_f32_e32 v93, 0x3fb8aa3b, v91
	v_mul_f32_e32 v91, 0x3fb8aa3b, v122
	v_mul_f32_e32 v92, 0x3fb8aa3b, v92
	v_exp_f32_e32 v90, v90
	v_exp_f32_e32 v91, v91
	v_sub_f32_e32 v78, v76, v77
	v_exp_f32_e32 v92, v92
	v_exp_f32_e32 v93, v93
	v_mul_f32_e32 v78, 0x3fb8aa3b, v78
	v_exp_f32_e32 v78, v78
	v_pk_add_f32 v[90:91], v[90:91], 1.0 op_sel_hi:[1,0] neg_lo:[1,0] neg_hi:[1,0]
	v_lshlrev_b32_e32 v72, 16, v72
	v_pk_mul_f32 v[90:91], v[90:91], v[92:93]
	v_mul_f32_e32 v72, v137, v72
	v_cvt_pk_bf16_f32 v92, v90, s0
	ds_write_b16 v117, v92 offset:8704
	v_mul_f32_e32 v92, v90, v78
	v_mul_f32_e32 v93, v91, v78
	v_cvt_pk_bf16_f32 v90, v72, s0
	ds_write_b16 v117, v90 offset:272
	v_cvt_pk_bf16_f32 v90, v91, s0
	v_add_f32_e32 v91, v95, v123
	ds_write_b16 v117, v90 offset:8976
	v_mul_f32_e32 v72, v94, v72
	v_sub_f32_e32 v90, v91, v77
	v_cvt_pk_bf16_f32 v72, v72, s0
	v_mul_f32_e32 v90, 0x3fb8aa3b, v90
	ds_write_b16 v117, v72 offset:17680
	v_cvt_pk_bf16_f32 v72, v92, v93
	v_exp_f32_e32 v93, v90
	v_lshlrev_b32_e32 v89, 16, v89
	v_sub_f32_e32 v90, v77, v91
	v_mul_f32_e32 v92, 0x3fb8aa3b, v123
	v_mul_f32_e32 v89, v93, v89
	v_cvt_pk_bf16_f32 v93, v89, s0
	v_mul_f32_e32 v89, v94, v89
	v_cvt_pk_bf16_f32 v89, v89, s0
	ds_write_b16 v117, v89 offset:17952
	v_add_f32_e32 v89, v91, v124
	v_sub_f32_e32 v91, v89, v77
	v_mul_f32_e32 v91, 0x3fb8aa3b, v91
	ds_write_b16 v117, v93 offset:544
	v_exp_f32_e32 v95, v91
	v_sub_f32_e32 v91, v77, v89
	v_mul_f32_e32 v93, 0x3fb8aa3b, v124
	v_mul_f32_e32 v90, 0x3fb8aa3b, v90
	v_exp_f32_e32 v92, v92
	v_mul_f32_e32 v91, 0x3fb8aa3b, v91
	v_exp_f32_e32 v93, v93
	v_exp_f32_e32 v90, v90
	v_exp_f32_e32 v91, v91
	v_lshlrev_b32_e32 v73, 16, v73
	v_pk_add_f32 v[92:93], v[92:93], 1.0 op_sel_hi:[1,0] neg_lo:[1,0] neg_hi:[1,0]
	v_mul_f32_e32 v73, v95, v73
	v_pk_mul_f32 v[90:91], v[92:93], v[90:91]
	v_add_f32_e32 v89, v89, v125
	v_cvt_pk_bf16_f32 v92, v90, s0
	ds_write_b16 v117, v92 offset:9248
	v_mul_f32_e32 v92, v90, v78
	v_mul_f32_e32 v93, v91, v78
	v_cvt_pk_bf16_f32 v90, v73, s0
	ds_write_b16 v117, v90 offset:816
	v_cvt_pk_bf16_f32 v90, v91, s0
	ds_write_b16 v117, v90 offset:9520
	v_sub_f32_e32 v90, v89, v77
	v_mul_f32_e32 v90, 0x3fb8aa3b, v90
	v_exp_f32_e32 v91, v90
	v_mul_f32_e32 v73, v94, v73
	v_cvt_pk_bf16_f32 v73, v73, s0
	ds_write_b16 v117, v73 offset:18224
	v_cvt_pk_bf16_f32 v73, v92, v93
	v_lshlrev_b32_e32 v92, 16, v88
	v_mul_f32_e32 v91, v91, v92
	v_cvt_pk_bf16_f32 v92, v91, s0
	ds_write_b16 v117, v92 offset:1088
	v_add_f32_e32 v92, v89, v126
	v_sub_f32_e32 v90, v77, v89
	v_sub_f32_e32 v89, v92, v77
	v_mul_f32_e32 v91, v94, v91
	v_mul_f32_e32 v89, 0x3fb8aa3b, v89
	v_cvt_pk_bf16_f32 v91, v91, s0
	v_exp_f32_e32 v93, v89
	v_sub_f32_e32 v89, v77, v92
	v_mul_f32_e32 v88, 0x3fb8aa3b, v125
	ds_write_b16 v117, v91 offset:18496
	v_mul_f32_e32 v91, 0x3fb8aa3b, v89
	v_mul_f32_e32 v89, 0x3fb8aa3b, v126
	v_mul_f32_e32 v90, 0x3fb8aa3b, v90
	v_exp_f32_e32 v88, v88
	v_exp_f32_e32 v89, v89
	v_exp_f32_e32 v90, v90
	v_exp_f32_e32 v91, v91
	v_lshlrev_b32_e32 v74, 16, v74
	v_pk_add_f32 v[88:89], v[88:89], 1.0 op_sel_hi:[1,0] neg_lo:[1,0] neg_hi:[1,0]
	v_mul_f32_e32 v74, v93, v74
	v_pk_mul_f32 v[88:89], v[88:89], v[90:91]
	v_lshlrev_b32_e32 v87, 16, v87
	v_cvt_pk_bf16_f32 v90, v88, s0
	ds_write_b16 v117, v90 offset:9792
	v_mul_f32_e32 v90, v88, v78
	v_mul_f32_e32 v91, v89, v78
	v_cvt_pk_bf16_f32 v88, v74, s0
	ds_write_b16 v117, v88 offset:1360
	v_cvt_pk_bf16_f32 v88, v89, s0
	v_add_f32_e32 v89, v92, v127
	ds_write_b16 v117, v88 offset:10064
	v_mul_f32_e32 v74, v94, v74
	v_sub_f32_e32 v88, v89, v77
	v_cvt_pk_bf16_f32 v74, v74, s0
	v_mul_f32_e32 v88, 0x3fb8aa3b, v88
	ds_write_b16 v117, v74 offset:18768
	v_cvt_pk_bf16_f32 v74, v90, v91
	v_exp_f32_e32 v91, v88
	v_sub_f32_e32 v88, v77, v89
	v_mul_f32_e32 v90, 0x3fb8aa3b, v127
	v_mul_f32_e32 v88, 0x3fb8aa3b, v88
	v_mul_f32_e32 v87, v91, v87
	v_cvt_pk_bf16_f32 v91, v87, s0
	v_mul_f32_e32 v87, v94, v87
	v_cvt_pk_bf16_f32 v87, v87, s0
	ds_write_b16 v117, v87 offset:19040
	v_add_f32_e32 v87, v89, v128
	v_sub_f32_e32 v89, v87, v77
	v_mul_f32_e32 v89, 0x3fb8aa3b, v89
	ds_write_b16 v117, v91 offset:1632
	v_exp_f32_e32 v92, v89
	v_sub_f32_e32 v89, v77, v87
	v_mul_f32_e32 v91, 0x3fb8aa3b, v128
	v_exp_f32_e32 v90, v90
	v_mul_f32_e32 v89, 0x3fb8aa3b, v89
	v_exp_f32_e32 v91, v91
	v_exp_f32_e32 v88, v88
	v_exp_f32_e32 v89, v89
	v_lshlrev_b32_e32 v75, 16, v75
	v_pk_add_f32 v[90:91], v[90:91], 1.0 op_sel_hi:[1,0] neg_lo:[1,0] neg_hi:[1,0]
	v_mul_f32_e32 v75, v92, v75
	v_pk_mul_f32 v[88:89], v[90:91], v[88:89]
	v_add_f32_e32 v87, v87, v129
	v_cvt_pk_bf16_f32 v90, v88, s0
	ds_write_b16 v117, v90 offset:10336
	v_mul_f32_e32 v90, v88, v78
	v_mul_f32_e32 v91, v89, v78
	v_cvt_pk_bf16_f32 v88, v75, s0
	ds_write_b16 v117, v88 offset:1904
	v_cvt_pk_bf16_f32 v88, v89, s0
	ds_write_b16 v117, v88 offset:10608
	v_sub_f32_e32 v88, v87, v77
	v_mul_f32_e32 v88, 0x3fb8aa3b, v88
	v_exp_f32_e32 v89, v88
	v_mul_f32_e32 v75, v94, v75
	v_cvt_pk_bf16_f32 v75, v75, s0
	ds_write_b16 v117, v75 offset:19312
	v_cvt_pk_bf16_f32 v75, v90, v91
	v_lshlrev_b32_e32 v90, 16, v86
	v_mul_f32_e32 v89, v89, v90
; DI u32 pack2bf(float lo, float hi) { f32x2 v = {lo, hi}; return __builtin_bit_cast(u32, __builtin_convertvector(v, bf2_t)); }
; DI u16 f2bf(float x) { return (u16)(pack2bf(x, 0.f) & 0xffffu); }
; DI float bf2f(u16 b) { return __uint_as_float(((u32)b) << 16); }
; template <int PASS>
; DI void hgrn_unit(const Params& p, int layer, int unit, char* smem) {
;     ...
;       const float Emid = __expf(bmid), Elm = __expf(blast - bmid);
; #pragma unroll
;       for (int jj = 0; jj < 16; jj += 2) {
;         float kl2[2];
; #pragma unroll
;         for (int u = 0; u < 2; ++u) {
;           const int j = half * 16 + jj + u;
;           run += gval[jj + u];
;           float e1 = __expf(run - bmid), e2 = __expf(bmid - run);
;           float q = bf2f(qraw[jj + u]);
;           float k = 1.f - __expf(gval[jj + u]);
;           float qm = q * e1, km = k * e2;
;           kl2[u] = km * Elm;
;           sQm[j * HS + d] = f2bf(qm); sKm[j * HS + d] = f2bf(km); sQb[j * HS + d] = f2bf(qm * Emid);
;         }
;         klp[jj >> 1] = pack2bf(kl2[0], kl2[1]);
;       }
;     } else {
; #pragma unroll
;       for (int jj = 0; jj < 16; jj += 2) {
;         float kl2[2];
; #pragma unroll
;         for (int u = 0; u < 2; ++u) {
;           run += gval[jj + u];
;           kl2[u] = (1.f - __expf(gval[jj + u])) * __expf(blast - run);
;         }
;         klp[jj >> 1] = pack2bf(kl2[0], kl2[1]);
;       }
;     }
; #pragma unroll
;     for (int jj = 0; jj < 16; jj += 2)
;       vtp[jj >> 1] = (u32)vraw[jj] | ((u32)vraw[jj + 1] << 16);
;     {
;       u32x4 a = {klp[0], klp[1], klp[2], klp[3]}, b = {klp[4], klp[5], klp[6], klp[7]};
;       *(u32x4*)(sKlT + d * VS + half * 16) = a; *(u32x4*)(sKlT + d * VS + half * 16 + 8) = b;
;       u32x4 c0 = {vtp[0], vtp[1], vtp[2], vtp[3]}, c1 = {vtp[4], vtp[5], vtp[6], vtp[7]};
;       *(u32x4*)(sVt + d * VS + half * 16) = c0; *(u32x4*)(sVt + d * VS + half * 16 + 8) = c1;
;     }
;     if (half) sDec[d] = __expf(blast);
	v_cvt_pk_bf16_f32 v90, v89, s0
	ds_write_b16 v117, v90 offset:2176
	v_add_f32_e32 v90, v87, v130
	v_sub_f32_e32 v88, v77, v87
	v_sub_f32_e32 v87, v90, v77
	v_mul_f32_e32 v89, v94, v89
	v_mul_f32_e32 v87, 0x3fb8aa3b, v87
	v_cvt_pk_bf16_f32 v89, v89, s0
	v_exp_f32_e32 v91, v87
	v_sub_f32_e32 v87, v77, v90
	v_mul_f32_e32 v86, 0x3fb8aa3b, v129
	ds_write_b16 v117, v89 offset:19584
	v_mul_f32_e32 v89, 0x3fb8aa3b, v87
	v_mul_f32_e32 v87, 0x3fb8aa3b, v130
	v_mul_f32_e32 v88, 0x3fb8aa3b, v88
	v_exp_f32_e32 v86, v86
	v_exp_f32_e32 v87, v87
	v_exp_f32_e32 v88, v88
	v_exp_f32_e32 v89, v89
	v_lshlrev_b32_e32 v85, 16, v85
	v_pk_add_f32 v[86:87], v[86:87], 1.0 op_sel_hi:[1,0] neg_lo:[1,0] neg_hi:[1,0]
	v_mul_f32_e32 v85, v91, v85
	v_pk_mul_f32 v[86:87], v[86:87], v[88:89]
	v_lshlrev_b32_e32 v83, 16, v83
	v_cvt_pk_bf16_f32 v88, v86, s0
	ds_write_b16 v117, v88 offset:10880
	v_mul_f32_e32 v88, v86, v78
	v_mul_f32_e32 v89, v87, v78
	v_cvt_pk_bf16_f32 v86, v85, s0
	v_mul_f32_e32 v85, v94, v85
	v_cvt_pk_bf16_f32 v85, v85, s0
	ds_write_b16 v117, v85 offset:19856
	v_add_f32_e32 v85, v90, v131
	ds_write_b16 v117, v86 offset:2448
	v_cvt_pk_bf16_f32 v86, v87, s0
	v_sub_f32_e32 v87, v85, v77
	v_mul_f32_e32 v87, 0x3fb8aa3b, v87
	v_exp_f32_e32 v87, v87
	ds_write_b16 v117, v86 offset:11152
	v_cvt_pk_bf16_f32 v86, v88, v89
	v_lshlrev_b32_e32 v89, 16, v84
	v_mul_f32_e32 v87, v87, v89
	v_add_f32_e32 v90, v85, v132
	v_sub_f32_e32 v88, v77, v85
	v_cvt_pk_bf16_f32 v89, v87, s0
	v_mul_f32_e32 v87, v94, v87
	v_sub_f32_e32 v85, v90, v77
	v_cvt_pk_bf16_f32 v87, v87, s0
	v_mul_f32_e32 v85, 0x3fb8aa3b, v85
	ds_write_b16 v117, v87 offset:20128
	v_exp_f32_e32 v87, v85
	v_sub_f32_e32 v85, v77, v90
	v_mul_f32_e32 v84, 0x3fb8aa3b, v131
	ds_write_b16 v117, v89 offset:2720
	v_mul_f32_e32 v89, 0x3fb8aa3b, v85
	v_mul_f32_e32 v85, 0x3fb8aa3b, v132
	v_mul_f32_e32 v88, 0x3fb8aa3b, v88
	v_exp_f32_e32 v84, v84
	v_exp_f32_e32 v85, v85
	v_exp_f32_e32 v88, v88
	v_exp_f32_e32 v89, v89
	v_mul_f32_e32 v83, v87, v83
	v_pk_add_f32 v[84:85], v[84:85], 1.0 op_sel_hi:[1,0] neg_lo:[1,0] neg_hi:[1,0]
	v_lshlrev_b32_e32 v81, 16, v81
	v_pk_mul_f32 v[84:85], v[84:85], v[88:89]
	v_or_b32_sdwa v67, v67, v70 dst_sel:DWORD dst_unused:UNUSED_PAD src0_sel:DWORD src1_sel:WORD_0
	v_cvt_pk_bf16_f32 v87, v84, s0
	v_mul_f32_e32 v88, v84, v78
	v_mul_f32_e32 v89, v85, v78
	v_cvt_pk_bf16_f32 v84, v83, s0
	v_mul_f32_e32 v83, v94, v83
	v_cvt_pk_bf16_f32 v83, v83, s0
	ds_write_b16 v117, v84 offset:2992
	v_cvt_pk_bf16_f32 v84, v85, s0
	ds_write_b16 v117, v83 offset:20400
	v_add_f32_e32 v83, v90, v133
	ds_write_b16 v117, v84 offset:11696
	v_sub_f32_e32 v84, v83, v77
	v_mul_f32_e32 v84, 0x3fb8aa3b, v84
	v_exp_f32_e32 v85, v84
	ds_write_b16 v117, v87 offset:11424
	v_cvt_pk_bf16_f32 v87, v88, v89
	v_lshlrev_b32_e32 v88, 16, v82
	v_add_f32_e32 v89, v83, v136
	v_sub_f32_e32 v84, v77, v83
	v_mul_f32_e32 v85, v85, v88
	v_sub_f32_e32 v83, v89, v77
	v_cvt_pk_bf16_f32 v88, v85, s0
	v_mul_f32_e32 v85, v94, v85
	v_mul_f32_e32 v83, 0x3fb8aa3b, v83
	ds_write_b16 v117, v88 offset:3264
	v_cvt_pk_bf16_f32 v85, v85, s0
	v_exp_f32_e32 v88, v83
	v_sub_f32_e32 v83, v77, v89
	v_mul_f32_e32 v82, 0x3fb8aa3b, v133
	ds_write_b16 v117, v85 offset:20672
	v_mul_f32_e32 v85, 0x3fb8aa3b, v83
	v_mul_f32_e32 v83, 0x3fb8aa3b, v136
	v_mul_f32_e32 v84, 0x3fb8aa3b, v84
	v_exp_f32_e32 v82, v82
	v_exp_f32_e32 v83, v83
	v_exp_f32_e32 v84, v84
	v_exp_f32_e32 v85, v85
	v_mul_f32_e32 v81, v88, v81
	v_pk_add_f32 v[82:83], v[82:83], 1.0 op_sel_hi:[1,0] neg_lo:[1,0] neg_hi:[1,0]
	v_lshlrev_b32_e32 v70, 16, v142
	v_pk_mul_f32 v[82:83], v[82:83], v[84:85]
	v_lshlrev_b32_e32 v71, 16, v143
	v_cvt_pk_bf16_f32 v84, v82, s0
	ds_write_b16 v117, v84 offset:11968
	v_mul_f32_e32 v84, v82, v78
	v_mul_f32_e32 v85, v83, v78
	v_cvt_pk_bf16_f32 v82, v81, s0
	v_mul_f32_e32 v81, v94, v81
	v_cvt_pk_bf16_f32 v81, v81, s0
	ds_write_b16 v117, v82 offset:3536
	v_cvt_pk_bf16_f32 v82, v83, s0
	ds_write_b16 v117, v81 offset:20944
	v_add_f32_e32 v81, v89, v135
	ds_write_b16 v117, v82 offset:12240
	v_sub_f32_e32 v82, v81, v77
	v_mul_f32_e32 v82, 0x3fb8aa3b, v82
	v_exp_f32_e32 v83, v82
	v_cvt_pk_bf16_f32 v88, v84, v85
	v_lshlrev_b32_e32 v84, 16, v80
	v_sub_f32_e32 v82, v77, v81
	v_mul_f32_e32 v83, v83, v84
	v_cvt_pk_bf16_f32 v84, v83, s0
	v_mul_f32_e32 v83, v94, v83
	v_cvt_pk_bf16_f32 v83, v83, s0
	v_add_f32_e32 v81, v81, v134
	v_mul_f32_e32 v80, 0x3fb8aa3b, v135
	ds_write_b16 v117, v83 offset:21216
	v_sub_f32_e32 v83, v81, v77
	v_sub_f32_e32 v77, v77, v81
	v_mul_f32_e32 v81, 0x3fb8aa3b, v134
	v_mul_f32_e32 v82, 0x3fb8aa3b, v82
	v_exp_f32_e32 v80, v80
	v_mul_f32_e32 v83, 0x3fb8aa3b, v83
	v_mul_f32_e32 v77, 0x3fb8aa3b, v77
	v_exp_f32_e32 v81, v81
	v_exp_f32_e32 v82, v82
	ds_write_b16 v117, v84 offset:3808
	v_exp_f32_e32 v84, v83
	v_exp_f32_e32 v83, v77
	v_pk_add_f32 v[80:81], v[80:81], 1.0 op_sel_hi:[1,0] neg_lo:[1,0] neg_hi:[1,0]
	v_lshlrev_b32_e32 v77, 16, v79
	v_mul_f32_e32 v77, v84, v77
	v_pk_mul_f32 v[80:81], v[80:81], v[82:83]
	v_or_b32_sdwa v70, v70, v138 dst_sel:DWORD dst_unused:UNUSED_PAD src0_sel:DWORD src1_sel:WORD_0
	v_cvt_pk_bf16_f32 v79, v80, s0
	ds_write_b16 v117, v79 offset:12512
	v_pk_mul_f32 v[78:79], v[78:79], v[80:81] op_sel_hi:[0,1]
	v_cvt_pk_bf16_f32 v80, v77, s0
	v_mul_f32_e32 v77, v94, v77
	ds_write_b16 v117, v80 offset:4080
	v_cvt_pk_bf16_f32 v80, v81, s0
	v_cvt_pk_bf16_f32 v77, v77, s0
	v_or_b32_sdwa v71, v71, v139 dst_sel:DWORD dst_unused:UNUSED_PAD src0_sel:DWORD src1_sel:WORD_0
	ds_write_b16 v117, v80 offset:12784
	ds_write_b16 v117, v77 offset:21488
	v_cvt_pk_bf16_f32 v89, v78, v79
	ds_write_b128 v104, v[72:75] offset:26112
	ds_write_b128 v104, v[86:89] offset:26128
	ds_write_b128 v104, v[64:67] offset:36352
	ds_write_b128 v104, v[68:71] offset:36368
	s_and_saveexec_b64 s[74:75], s[4:5]
	s_cbranch_execz .LBB0_608
	v_mul_f32_e32 v64, 0x3fb8aa3b, v76
	v_exp_f32_e32 v64, v64
	ds_write_b32 v105, v64 offset:46592

; DI u32 pack2bf(float lo, float hi) { f32x2 v = {lo, hi}; return __builtin_bit_cast(u32, __builtin_convertvector(v, bf2_t)); }
; DI float bflo(u32 w) { return __uint_as_float(w << 16); }
; DI float bfhi(u32 w) { return __uint_as_float(w & 0xffff0000u); }
; DI float xhalf(float v) { return __shfl_xor(v, 32); }
; template <int NKS>
; DI void attn_tile(const Params& p, int layer, int seq, int slot, int qt, char* smem, bool wr = true) {
;     ...
;   if (GQA) {
;     const u16* gate = (const u16*)(p.out + DO_GB) + hd * 64;
; #pragma unroll
;     for (int qb = 0; qb < 2; ++qb) {
;       const float inv = 1.f / (lsum[qb] + xhalf(lsum[qb]));
;       const size_t t = (size_t)(q0 + 32 * qb + r);
; #pragma unroll
;       for (int eb = 0; eb < 2; ++eb)
; #pragma unroll
;         for (int g = 0; g < 4; ++g) {
;           int e = 32 * eb + 8 * g + 4 * h;
;           u32x2 gt = *(const u32x2*)(gate + t * 256 + e);
;           u32x2 o = {pack2bf(O[qb][eb][4 * g] * inv * bflo(gt[0]), O[qb][eb][4 * g + 1] * inv * bfhi(gt[0])),
;                      pack2bf(O[qb][eb][4 * g + 2] * inv * bflo(gt[1]), O[qb][eb][4 * g + 3] * inv * bfhi(gt[1]))};
;           if (wr) *(u32x2*)(Qb + t * 256 + e) = o;
;         }
.LBB0_613:
	s_or_b64 exec, exec, s[4:5]
	v_readlane_b32 s0, v249, 22
	v_readlane_b32 s1, v249, 23
	s_add_u32 s0, s0, s16
	s_addc_u32 s1, s1, s17
	v_lshl_add_u64 v[64:65], s[0:1], 0, v[178:179]
	v_lshlrev_b32_e32 v128, 3, v183
	v_lshl_add_u64 v[66:67], v[64:65], 0, v[128:129]
	s_waitcnt vmcnt(0)
	s_barrier
	global_load_dwordx2 v[72:73], v[66:67], off
	global_load_dwordx2 v[74:75], v[66:67], off offset:16
	global_load_dwordx2 v[76:77], v[66:67], off offset:32
	global_load_dwordx2 v[78:79], v[66:67], off offset:48
	global_load_dwordx2 v[80:81], v[66:67], off offset:64
	global_load_dwordx2 v[82:83], v[66:67], off offset:80
	global_load_dwordx2 v[84:85], v[66:67], off offset:96
	global_load_dwordx2 v[86:87], v[66:67], off offset:112
	ds_bpermute_b32 v70, v235, v115
	v_lshl_add_u64 v[68:69], s[0:1], 0, v[176:177]
	v_lshl_add_u64 v[64:65], s[6:7], 0, v[178:179]
	v_lshl_add_u64 v[64:65], v[64:65], 0, v[128:129]
	v_lshl_add_u64 v[68:69], v[68:69], 0, v[128:129]
	s_waitcnt lgkmcnt(0)
	v_add_f32_e32 v88, v115, v70
	v_div_scale_f32 v89, s[0:1], v88, v88, 1.0
	v_rcp_f32_e32 v90, v89
	v_div_scale_f32 v91, vcc, 1.0, v88, 1.0
	global_load_dwordx2 v[66:67], v[68:69], off
	global_load_dwordx2 v[70:71], v[68:69], off offset:16
	v_fma_f32 v92, -v89, v90, 1.0
	v_fmac_f32_e32 v90, v92, v90
	v_mul_f32_e32 v92, v91, v90
	v_fma_f32 v93, -v89, v92, v91
	v_fmac_f32_e32 v92, v93, v90
	v_fma_f32 v89, -v89, v92, v91
	v_div_fmas_f32 v89, v89, v90, v92
	v_div_fixup_f32 v88, v89, v88, 1.0
	v_mul_f32_e32 v48, v48, v88
	v_mul_f32_e32 v49, v49, v88
	v_mul_f32_e32 v50, v50, v88
	v_mul_f32_e32 v51, v51, v88
	v_mul_f32_e32 v52, v52, v88
	v_mul_f32_e32 v53, v53, v88
	v_mul_f32_e32 v54, v54, v88
	v_mul_f32_e32 v55, v55, v88
	v_mul_f32_e32 v56, v56, v88
	v_mul_f32_e32 v57, v57, v88
	v_mul_f32_e32 v58, v58, v88
	v_mul_f32_e32 v59, v59, v88
	v_mul_f32_e32 v60, v60, v88
	v_mul_f32_e32 v61, v61, v88
	v_mul_f32_e32 v62, v62, v88
	v_mul_f32_e32 v63, v63, v88
	v_mul_f32_e32 v32, v32, v88
	v_mul_f32_e32 v33, v33, v88
	v_mul_f32_e32 v34, v34, v88
	v_mul_f32_e32 v35, v35, v88
	s_waitcnt vmcnt(9)
	v_lshlrev_b32_e32 v90, 16, v72
	v_and_b32_e32 v91, 0xffff0000, v72
	v_lshlrev_b32_e32 v72, 16, v73
	v_and_b32_e32 v73, 0xffff0000, v73
	s_waitcnt vmcnt(8)
	v_lshlrev_b32_e32 v92, 16, v74
	v_and_b32_e32 v93, 0xffff0000, v74
	v_lshlrev_b32_e32 v74, 16, v75
	v_and_b32_e32 v75, 0xffff0000, v75
	s_waitcnt vmcnt(7)
	v_lshlrev_b32_e32 v94, 16, v76
	v_and_b32_e32 v95, 0xffff0000, v76
	v_lshlrev_b32_e32 v76, 16, v77
	v_and_b32_e32 v77, 0xffff0000, v77
	s_waitcnt vmcnt(6)
	v_lshlrev_b32_e32 v96, 16, v78
	v_and_b32_e32 v97, 0xffff0000, v78
	v_lshlrev_b32_e32 v78, 16, v79
	v_and_b32_e32 v79, 0xffff0000, v79
	v_pk_mul_f32 v[48:49], v[48:49], v[90:91]
	v_pk_mul_f32 v[50:51], v[50:51], v[72:73]
	v_pk_mul_f32 v[52:53], v[52:53], v[92:93]
	v_pk_mul_f32 v[54:55], v[54:55], v[74:75]
	v_pk_mul_f32 v[56:57], v[56:57], v[94:95]
	v_pk_mul_f32 v[58:59], v[58:59], v[76:77]
	v_pk_mul_f32 v[60:61], v[60:61], v[96:97]
	v_pk_mul_f32 v[62:63], v[62:63], v[78:79]
	v_cvt_pk_bf16_f32 v48, v48, v49
	v_cvt_pk_bf16_f32 v49, v50, v51
	s_waitcnt vmcnt(5)
	v_lshlrev_b32_e32 v98, 16, v80
	v_and_b32_e32 v99, 0xffff0000, v80
	v_cvt_pk_bf16_f32 v50, v52, v53
	v_cvt_pk_bf16_f32 v51, v54, v55
	v_cvt_pk_bf16_f32 v52, v56, v57
	v_cvt_pk_bf16_f32 v53, v58, v59
	v_cvt_pk_bf16_f32 v54, v60, v61
	v_cvt_pk_bf16_f32 v55, v62, v63
	global_store_dwordx2 v[64:65], v[48:49], off
	global_store_dwordx2 v[64:65], v[50:51], off offset:16
	global_store_dwordx2 v[64:65], v[52:53], off offset:32
	global_store_dwordx2 v[64:65], v[54:55], off offset:48
	v_lshlrev_b32_e32 v48, 16, v81
	v_and_b32_e32 v49, 0xffff0000, v81
	v_pk_mul_f32 v[32:33], v[32:33], v[98:99]
	v_pk_mul_f32 v[34:35], v[34:35], v[48:49]
	v_cvt_pk_bf16_f32 v32, v32, v33
	v_cvt_pk_bf16_f32 v33, v34, v35
	v_mul_f32_e32 v34, v36, v88
	v_mul_f32_e32 v35, v37, v88
	s_waitcnt vmcnt(8)
	v_lshlrev_b32_e32 v36, 16, v82
	v_and_b32_e32 v37, 0xffff0000, v82
	v_pk_mul_f32 v[34:35], v[34:35], v[36:37]
	v_mul_f32_e32 v36, v38, v88
	v_mul_f32_e32 v37, v39, v88
	v_lshlrev_b32_e32 v38, 16, v83
	v_and_b32_e32 v39, 0xffff0000, v83
	v_pk_mul_f32 v[36:37], v[36:37], v[38:39]
	v_cvt_pk_bf16_f32 v34, v34, v35
	v_cvt_pk_bf16_f32 v35, v36, v37
	global_store_dwordx2 v[64:65], v[34:35], off offset:80
	v_mul_f32_e32 v34, v40, v88
	v_mul_f32_e32 v35, v41, v88
	s_waitcnt vmcnt(8)
	v_lshlrev_b32_e32 v38, 16, v84
	v_and_b32_e32 v39, 0xffff0000, v84
	v_pk_mul_f32 v[34:35], v[34:35], v[38:39]
	v_mul_f32_e32 v38, v42, v88
	v_mul_f32_e32 v39, v43, v88
	v_lshlrev_b32_e32 v40, 16, v85
	v_and_b32_e32 v41, 0xffff0000, v85
	v_pk_mul_f32 v[38:39], v[38:39], v[40:41]
	v_cvt_pk_bf16_f32 v34, v34, v35
	v_cvt_pk_bf16_f32 v35, v38, v39
	global_store_dwordx2 v[64:65], v[32:33], off offset:64
	global_load_dwordx2 v[32:33], v[68:69], off offset:32
	s_waitcnt vmcnt(9)
; DI u32 pack2bf(float lo, float hi) { f32x2 v = {lo, hi}; return __builtin_bit_cast(u32, __builtin_convertvector(v, bf2_t)); }
; DI float bflo(u32 w) { return __uint_as_float(w << 16); }
; DI float bfhi(u32 w) { return __uint_as_float(w & 0xffff0000u); }
; DI float xhalf(float v) { return __shfl_xor(v, 32); }
; template <int NKS>
; DI void attn_tile(const Params& p, int layer, int seq, int slot, int qt, char* smem, bool wr = true) {
;     ...
; #pragma unroll
;     for (int qb = 0; qb < 2; ++qb) {
;       const float inv = 1.f / (lsum[qb] + xhalf(lsum[qb]));
;       const size_t t = (size_t)(q0 + 32 * qb + r);
; #pragma unroll
;       for (int eb = 0; eb < 2; ++eb)
; #pragma unroll
;         for (int g = 0; g < 4; ++g) {
;           int e = 32 * eb + 8 * g + 4 * h;
;           u32x2 gt = *(const u32x2*)(gate + t * 256 + e);
;           u32x2 o = {pack2bf(O[qb][eb][4 * g] * inv * bflo(gt[0]), O[qb][eb][4 * g + 1] * inv * bfhi(gt[0])),
;                      pack2bf(O[qb][eb][4 * g + 2] * inv * bflo(gt[1]), O[qb][eb][4 * g + 3] * inv * bfhi(gt[1]))};
;           if (wr) *(u32x2*)(Qb + t * 256 + e) = o;
;         }
	v_lshlrev_b32_e32 v38, 16, v86
	global_store_dwordx2 v[64:65], v[34:35], off offset:96
	v_mul_f32_e32 v34, v44, v88
	v_mul_f32_e32 v35, v45, v88
	v_and_b32_e32 v39, 0xffff0000, v86
	v_pk_mul_f32 v[34:35], v[34:35], v[38:39]
	global_load_dwordx2 v[36:37], v[68:69], off offset:48
	global_load_dwordx2 v[40:41], v[68:69], off offset:64
	global_load_dwordx2 v[44:45], v[68:69], off offset:80
	v_cvt_pk_bf16_f32 v34, v34, v35
	ds_bpermute_b32 v35, v235, v114
	v_mul_f32_e32 v38, v46, v88
	v_mul_f32_e32 v39, v47, v88
	v_lshlrev_b32_e32 v42, 16, v87
	v_and_b32_e32 v43, 0xffff0000, v87
	v_pk_mul_f32 v[38:39], v[38:39], v[42:43]
	s_waitcnt lgkmcnt(0)
	v_add_f32_e32 v46, v114, v35
	v_div_scale_f32 v47, s[0:1], v46, v46, 1.0
	v_rcp_f32_e32 v48, v47
	v_cvt_pk_bf16_f32 v35, v38, v39
	global_store_dwordx2 v[64:65], v[34:35], off offset:112
	v_div_scale_f32 v38, vcc, 1.0, v46, 1.0
	v_fma_f32 v34, -v47, v48, 1.0
	v_fmac_f32_e32 v48, v34, v48
	v_mul_f32_e32 v39, v38, v48
	global_load_dwordx2 v[34:35], v[68:69], off offset:96
	v_fma_f32 v42, -v47, v39, v38
	v_fmac_f32_e32 v39, v42, v48
	v_fma_f32 v38, -v47, v39, v38
	v_div_fmas_f32 v38, v38, v48, v39
	v_div_fixup_f32 v38, v38, v46, 1.0
	global_load_dwordx2 v[46:47], v[68:69], off offset:112
	v_mul_f32_e32 v16, v16, v38
	v_mul_f32_e32 v17, v17, v38
	s_waitcnt vmcnt(15)
	v_lshlrev_b32_e32 v48, 16, v66
	v_and_b32_e32 v49, 0xffff0000, v66
	v_pk_mul_f32 v[16:17], v[16:17], v[48:49]
	v_mul_f32_e32 v18, v18, v38
	v_mul_f32_e32 v19, v19, v38
	v_lshlrev_b32_e32 v48, 16, v67
	v_and_b32_e32 v49, 0xffff0000, v67
	v_lshl_add_u64 v[42:43], s[6:7], 0, v[176:177]
	v_pk_mul_f32 v[18:19], v[18:19], v[48:49]
	v_cvt_pk_bf16_f32 v16, v16, v17
	v_cvt_pk_bf16_f32 v17, v18, v19
	v_lshl_add_u64 v[18:19], v[42:43], 0, v[128:129]
	global_store_dwordx2 v[18:19], v[16:17], off
	v_mul_f32_e32 v16, v20, v38
	v_mul_f32_e32 v17, v21, v38
	s_waitcnt vmcnt(15)
	v_lshlrev_b32_e32 v20, 16, v70
	v_and_b32_e32 v21, 0xffff0000, v70
	v_pk_mul_f32 v[16:17], v[16:17], v[20:21]
	v_mul_f32_e32 v20, v22, v38
	v_mul_f32_e32 v21, v23, v38
	v_lshlrev_b32_e32 v22, 16, v71
	v_and_b32_e32 v23, 0xffff0000, v71
	v_pk_mul_f32 v[20:21], v[20:21], v[22:23]
	v_cvt_pk_bf16_f32 v16, v16, v17
	v_cvt_pk_bf16_f32 v17, v20, v21
	global_store_dwordx2 v[18:19], v[16:17], off offset:16
	v_mul_f32_e32 v16, v24, v38
	v_mul_f32_e32 v17, v25, v38
	v_mul_f32_e32 v0, v0, v38
	v_mul_f32_e32 v1, v1, v38
	v_mul_f32_e32 v2, v2, v38
	v_mul_f32_e32 v3, v3, v38
	s_mov_b64 s[0:1], 0
	s_waitcnt vmcnt(9)
	v_lshlrev_b32_e32 v20, 16, v32
	v_and_b32_e32 v21, 0xffff0000, v32
	v_pk_mul_f32 v[16:17], v[16:17], v[20:21]
	v_mul_f32_e32 v20, v26, v38
	v_mul_f32_e32 v21, v27, v38
	v_lshlrev_b32_e32 v22, 16, v33
	v_and_b32_e32 v23, 0xffff0000, v33
	v_pk_mul_f32 v[20:21], v[20:21], v[22:23]
	v_cvt_pk_bf16_f32 v16, v16, v17
	v_cvt_pk_bf16_f32 v17, v20, v21
	global_store_dwordx2 v[18:19], v[16:17], off offset:32
	v_mul_f32_e32 v16, v28, v38
	v_mul_f32_e32 v17, v29, v38
	s_waitcnt vmcnt(8)
	v_lshlrev_b32_e32 v20, 16, v36
	v_and_b32_e32 v21, 0xffff0000, v36
	v_pk_mul_f32 v[16:17], v[16:17], v[20:21]
	v_mul_f32_e32 v20, v30, v38
	v_mul_f32_e32 v21, v31, v38
	v_lshlrev_b32_e32 v22, 16, v37
	v_and_b32_e32 v23, 0xffff0000, v37
	v_pk_mul_f32 v[20:21], v[20:21], v[22:23]
	v_cvt_pk_bf16_f32 v16, v16, v17
	v_cvt_pk_bf16_f32 v17, v20, v21
	global_store_dwordx2 v[18:19], v[16:17], off offset:48
	s_waitcnt vmcnt(8)
	v_lshlrev_b32_e32 v16, 16, v40
	v_and_b32_e32 v17, 0xffff0000, v40
	v_pk_mul_f32 v[0:1], v[0:1], v[16:17]
	v_lshlrev_b32_e32 v16, 16, v41
	v_and_b32_e32 v17, 0xffff0000, v41
	v_pk_mul_f32 v[2:3], v[2:3], v[16:17]
	v_cvt_pk_bf16_f32 v0, v0, v1
	v_cvt_pk_bf16_f32 v1, v2, v3
	global_store_dwordx2 v[18:19], v[0:1], off offset:64
	v_mul_f32_e32 v0, v4, v38
	v_mul_f32_e32 v1, v5, v38
	s_waitcnt vmcnt(8)
	v_lshlrev_b32_e32 v2, 16, v44
	v_and_b32_e32 v3, 0xffff0000, v44
	v_pk_mul_f32 v[0:1], v[0:1], v[2:3]
	v_mul_f32_e32 v2, v6, v38
	v_mul_f32_e32 v3, v7, v38
	v_lshlrev_b32_e32 v4, 16, v45
	v_and_b32_e32 v5, 0xffff0000, v45
	v_pk_mul_f32 v[2:3], v[2:3], v[4:5]
	v_cvt_pk_bf16_f32 v0, v0, v1
	v_cvt_pk_bf16_f32 v1, v2, v3
	global_store_dwordx2 v[18:19], v[0:1], off offset:80
	v_mul_f32_e32 v0, v8, v38
	v_mul_f32_e32 v1, v9, v38
	s_waitcnt vmcnt(7)
	v_lshlrev_b32_e32 v2, 16, v34
	v_and_b32_e32 v3, 0xffff0000, v34
	v_pk_mul_f32 v[0:1], v[0:1], v[2:3]
	v_mul_f32_e32 v2, v10, v38
	v_mul_f32_e32 v3, v11, v38
	v_lshlrev_b32_e32 v4, 16, v35
	v_and_b32_e32 v5, 0xffff0000, v35
	v_pk_mul_f32 v[2:3], v[2:3], v[4:5]
	v_cvt_pk_bf16_f32 v0, v0, v1
	v_cvt_pk_bf16_f32 v1, v2, v3
	global_store_dwordx2 v[18:19], v[0:1], off offset:96
	v_mul_f32_e32 v0, v12, v38
	v_mul_f32_e32 v1, v13, v38
	s_waitcnt vmcnt(7)
	v_lshlrev_b32_e32 v2, 16, v46
	v_and_b32_e32 v3, 0xffff0000, v46
	v_pk_mul_f32 v[0:1], v[0:1], v[2:3]
	v_mul_f32_e32 v2, v14, v38
	v_mul_f32_e32 v3, v15, v38
	v_lshlrev_b32_e32 v4, 16, v47
	v_and_b32_e32 v5, 0xffff0000, v47
	v_pk_mul_f32 v[2:3], v[2:3], v[4:5]
	v_cvt_pk_bf16_f32 v0, v0, v1
	v_cvt_pk_bf16_f32 v1, v2, v3
	global_store_dwordx2 v[18:19], v[0:1], off offset:112

; DI float xhalf(float v) { return __shfl_xor(v, 32); }
; template <int NKS>
; DI void attn_tile(const Params& p, int layer, int seq, int slot, int qt, char* smem, bool wr = true) {
;     ...
;     for (int qb = 0; qb < 2; ++qb) {
;       const float inv = 1.f / (lsum[qb] + xhalf(lsum[qb]));
;       if (sub == 1) {
; #pragma unroll
;         for (int eb = 0; eb < 2; ++eb)
; #pragma unroll
;           for (int i = 0; i < 16; ++i) xch[(qhalf * 32 + eb * 16 + i) * 64 + lane] = O[qb][eb][i] * inv;
;       }
;       __syncthreads();
;       if (sub == 0) {
;         float ss = 0.f;
; #pragma unroll
;         for (int eb = 0; eb < 2; ++eb)
; #pragma unroll
;           for (int i = 0; i < 16; ++i) {
;             float v = O[qb][eb][i] * inv - lam * xch[(qhalf * 32 + eb * 16 + i) * 64 + lane];
;             O[qb][eb][i] = v; ss += v * v;
;           }
;         ss += xhalf(ss);
;         const float rn = rsqrtf(ss * (1.f / 64.f) + EPS) * post;
.LBB0_682:
	v_readlane_b32 s0, v249, 16
	v_readlane_b32 s1, v249, 17
	s_add_u32 s0, s0, s18
	s_addc_u32 s1, s1, s19
	s_cmp_lt_u32 s28, 2
	v_lshlrev_b32_e32 v65, 2, v168
	s_cselect_b64 s[8:9], -1, 0
	s_cmp_gt_u32 s28, 1
	v_lshlrev_b32_e32 v128, 1, v65
	v_lshlrev_b32_e32 v65, 2, v65
	v_lshl_or_b32 v69, s28, 13, v66
	s_waitcnt lgkmcnt(0)
	s_barrier
	s_cbranch_scc1 .LBB0_684
	ds_read2st64_b32 v[76:77], v69 offset1:1
	ds_read2st64_b32 v[72:73], v69 offset0:2 offset1:3
	ds_read2st64_b32 v[78:79], v69 offset0:4 offset1:5
	ds_read2st64_b32 v[80:81], v69 offset0:6 offset1:7
	ds_read2st64_b32 v[82:83], v69 offset0:8 offset1:9
	ds_read2st64_b32 v[84:85], v69 offset0:10 offset1:11
	ds_read2st64_b32 v[86:87], v69 offset0:12 offset1:13
	ds_read2st64_b32 v[88:89], v69 offset0:14 offset1:15
	ds_read2st64_b32 v[90:91], v69 offset0:24 offset1:25
	ds_read2st64_b32 v[92:93], v69 offset0:26 offset1:27
	ds_read2st64_b32 v[66:67], v69 offset0:28 offset1:29
	ds_read2st64_b32 v[74:75], v69 offset0:30 offset1:31
	ds_read2st64_b32 v[94:95], v69 offset0:16 offset1:17
	ds_read2st64_b32 v[96:97], v69 offset0:18 offset1:19
	ds_read2st64_b32 v[98:99], v69 offset0:20 offset1:21
	ds_read2st64_b32 v[100:101], v69 offset0:22 offset1:23
	s_waitcnt vmcnt(0) lgkmcnt(5)
	v_pk_mul_f32 v[66:67], v[64:65], v[66:67] op_sel_hi:[0,1]
	v_pk_fma_f32 v[44:45], v[44:45], v[68:69], v[66:67] op_sel_hi:[1,0,1] neg_lo:[0,0,1] neg_hi:[0,0,1]
	s_waitcnt lgkmcnt(4)
	v_pk_mul_f32 v[66:67], v[64:65], v[74:75] op_sel_hi:[0,1]
	v_pk_fma_f32 v[46:47], v[46:47], v[68:69], v[66:67] op_sel_hi:[1,0,1] neg_lo:[0,0,1] neg_hi:[0,0,1]
	v_lshl_add_u64 v[66:67], s[0:1], 0, v[162:163]
	v_lshl_add_u64 v[66:67], v[66:67], 0, v[128:129]
	v_pk_mul_f32 v[72:73], v[64:65], v[72:73] op_sel_hi:[0,1]
	global_load_dwordx2 v[106:107], v[66:67], off
	v_pk_fma_f32 v[50:51], v[50:51], v[68:69], v[72:73] op_sel_hi:[1,0,1] neg_lo:[0,0,1] neg_hi:[0,0,1]
	global_load_dwordx4 v[72:75], v65, s[62:63]
	v_pk_mul_f32 v[76:77], v[64:65], v[76:77] op_sel_hi:[0,1]
	v_pk_fma_f32 v[48:49], v[48:49], v[68:69], v[76:77] op_sel_hi:[1,0,1] neg_lo:[0,0,1] neg_hi:[0,0,1]
	v_pk_mul_f32 v[80:81], v[64:65], v[80:81] op_sel_hi:[0,1]
	v_pk_mul_f32 v[76:77], v[48:49], v[48:49]
	v_pk_mul_f32 v[78:79], v[64:65], v[78:79] op_sel_hi:[0,1]
	v_pk_mul_f32 v[84:85], v[64:65], v[84:85] op_sel_hi:[0,1]
	v_pk_mul_f32 v[82:83], v[64:65], v[82:83] op_sel_hi:[0,1]
	v_pk_mul_f32 v[88:89], v[64:65], v[88:89] op_sel_hi:[0,1]
	v_pk_mul_f32 v[86:87], v[64:65], v[86:87] op_sel_hi:[0,1]
	s_waitcnt lgkmcnt(2)
	v_pk_mul_f32 v[96:97], v[64:65], v[96:97] op_sel_hi:[0,1]
	v_pk_mul_f32 v[94:95], v[64:65], v[94:95] op_sel_hi:[0,1]
	s_waitcnt lgkmcnt(0)
	v_pk_mul_f32 v[100:101], v[64:65], v[100:101] op_sel_hi:[0,1]
	v_pk_mul_f32 v[98:99], v[64:65], v[98:99] op_sel_hi:[0,1]
	v_pk_mul_f32 v[92:93], v[64:65], v[92:93] op_sel_hi:[0,1]
	v_pk_mul_f32 v[90:91], v[64:65], v[90:91] op_sel_hi:[0,1]
	v_pk_mul_f32 v[110:111], v[50:51], v[50:51]
	v_pk_fma_f32 v[54:55], v[54:55], v[68:69], v[80:81] op_sel_hi:[1,0,1] neg_lo:[0,0,1] neg_hi:[0,0,1]
	v_pk_fma_f32 v[52:53], v[52:53], v[68:69], v[78:79] op_sel_hi:[1,0,1] neg_lo:[0,0,1] neg_hi:[0,0,1]
	v_pk_fma_f32 v[58:59], v[58:59], v[68:69], v[84:85] op_sel_hi:[1,0,1] neg_lo:[0,0,1] neg_hi:[0,0,1]
	v_pk_fma_f32 v[56:57], v[56:57], v[68:69], v[82:83] op_sel_hi:[1,0,1] neg_lo:[0,0,1] neg_hi:[0,0,1]
	v_pk_fma_f32 v[62:63], v[62:63], v[68:69], v[88:89] op_sel_hi:[1,0,1] neg_lo:[0,0,1] neg_hi:[0,0,1]
	v_pk_fma_f32 v[60:61], v[60:61], v[68:69], v[86:87] op_sel_hi:[1,0,1] neg_lo:[0,0,1] neg_hi:[0,0,1]
	v_pk_fma_f32 v[96:97], v[34:35], v[68:69], v[96:97] op_sel_hi:[1,0,1] neg_lo:[0,0,1] neg_hi:[0,0,1]
	v_pk_fma_f32 v[94:95], v[32:33], v[68:69], v[94:95] op_sel_hi:[1,0,1] neg_lo:[0,0,1] neg_hi:[0,0,1]
	v_pk_fma_f32 v[38:39], v[38:39], v[68:69], v[100:101] op_sel_hi:[1,0,1] neg_lo:[0,0,1] neg_hi:[0,0,1]
	v_pk_fma_f32 v[36:37], v[36:37], v[68:69], v[98:99] op_sel_hi:[1,0,1] neg_lo:[0,0,1] neg_hi:[0,0,1]
	v_pk_fma_f32 v[42:43], v[42:43], v[68:69], v[92:93] op_sel_hi:[1,0,1] neg_lo:[0,0,1] neg_hi:[0,0,1]
	v_pk_fma_f32 v[40:41], v[40:41], v[68:69], v[90:91] op_sel_hi:[1,0,1] neg_lo:[0,0,1] neg_hi:[0,0,1]
	v_add_f32_e32 v68, v76, v77
	v_add_f32_e32 v68, v68, v110
	v_pk_mul_f32 v[78:79], v[52:53], v[52:53]
	v_add_f32_e32 v68, v68, v111
	v_add_f32_e32 v68, v68, v78
	v_pk_mul_f32 v[80:81], v[54:55], v[54:55]
	v_add_f32_e32 v68, v68, v79
	v_add_f32_e32 v68, v68, v80
	v_pk_mul_f32 v[82:83], v[56:57], v[56:57]
	v_add_f32_e32 v68, v68, v81
	v_add_f32_e32 v68, v68, v82
	v_pk_mul_f32 v[84:85], v[58:59], v[58:59]
	v_add_f32_e32 v68, v68, v83
	v_add_f32_e32 v68, v68, v84
	v_pk_mul_f32 v[86:87], v[60:61], v[60:61]
	v_add_f32_e32 v68, v68, v85
	v_add_f32_e32 v68, v68, v86
	v_pk_mul_f32 v[88:89], v[62:63], v[62:63]
	v_add_f32_e32 v68, v68, v87
	v_add_f32_e32 v68, v68, v88
	v_pk_mul_f32 v[32:33], v[94:95], v[94:95]
	v_add_f32_e32 v68, v68, v89
	v_add_f32_e32 v32, v68, v32
	v_pk_mul_f32 v[34:35], v[96:97], v[96:97]
	v_add_f32_e32 v32, v32, v33
	v_add_f32_e32 v32, v32, v34
	v_pk_mul_f32 v[98:99], v[36:37], v[36:37]
	v_add_f32_e32 v32, v32, v35
	v_add_f32_e32 v32, v32, v98
	v_pk_mul_f32 v[100:101], v[38:39], v[38:39]
	v_add_f32_e32 v32, v32, v99
	v_add_f32_e32 v32, v32, v100
	v_pk_mul_f32 v[90:91], v[40:41], v[40:41]
	v_add_f32_e32 v32, v32, v101
	v_add_f32_e32 v32, v32, v90
	v_pk_mul_f32 v[92:93], v[42:43], v[42:43]
	v_add_f32_e32 v32, v32, v91
	v_add_f32_e32 v32, v32, v92
	v_pk_mul_f32 v[102:103], v[44:45], v[44:45]
	v_add_f32_e32 v32, v32, v93
	v_add_f32_e32 v32, v32, v102
	v_pk_mul_f32 v[104:105], v[46:47], v[46:47]
	v_add_f32_e32 v32, v32, v103
	v_add_f32_e32 v32, v32, v104
	v_add_f32_e32 v34, v32, v105
	ds_bpermute_b32 v35, v235, v34
	v_lshl_add_u64 v[108:109], s[16:17], 0, v[162:163]
	v_lshl_add_u64 v[82:83], v[108:109], 0, v[128:129]
	global_load_dwordx2 v[76:77], v[66:67], off offset:16
	global_load_dwordx2 v[78:79], v[66:67], off offset:32
	global_load_dwordx2 v[80:81], v[66:67], off offset:48
	s_waitcnt vmcnt(4)
; DI u32 pack2bf(float lo, float hi) { f32x2 v = {lo, hi}; return __builtin_bit_cast(u32, __builtin_convertvector(v, bf2_t)); }
; DI float bflo(u32 w) { return __uint_as_float(w << 16); }
; DI float bfhi(u32 w) { return __uint_as_float(w & 0xffff0000u); }
; DI float xhalf(float v) { return __shfl_xor(v, 32); }
; template <int NKS>
; DI void attn_tile(const Params& p, int layer, int seq, int slot, int qt, char* smem, bool wr = true) {
;     ...
;         ss += xhalf(ss);
;         const float rn = rsqrtf(ss * (1.f / 64.f) + EPS) * post;
;         const size_t t = (size_t)(q0 + 32 * qb + r);
; #pragma unroll
;         for (int eb = 0; eb < 2; ++eb)
; #pragma unroll
;           for (int g = 0; g < 4; ++g) {
;             int e = 32 * eb + 8 * g + 4 * h;
;             u32x2 gt = *(const u32x2*)(gate + t * 256 + e);
;             float4 nw = *(const float4*)(dnw + e);
;             u32x2 o = {pack2bf(O[qb][eb][4 * g] * rn * nw.x * bflo(gt[0]), O[qb][eb][4 * g + 1] * rn * nw.y * bfhi(gt[0])),
;                        pack2bf(O[qb][eb][4 * g + 2] * rn * nw.z * bflo(gt[1]), O[qb][eb][4 * g + 3] * rn * nw.w * bfhi(gt[1]))};
;             if (wr) *(u32x2*)(outb + t * 256 + e) = o;
;           }
	v_lshlrev_b32_e32 v32, 16, v106
	s_waitcnt lgkmcnt(0)
	v_add_f32_e32 v34, v34, v35
	v_fmamk_f32 v34, v34, 0x3c800000, v166
	v_mul_f32_e32 v35, 0x4b800000, v34
	v_cmp_gt_f32_e32 vcc, s27, v34
	v_and_b32_e32 v33, 0xffff0000, v106
	s_nop 0
	v_cndmask_b32_e32 v34, v34, v35, vcc
	v_rsq_f32_e32 v68, v34
	v_lshlrev_b32_e32 v34, 16, v107
	v_and_b32_e32 v35, 0xffff0000, v107
	v_mul_f32_e32 v71, 0x45800000, v68
	v_cndmask_b32_e32 v68, v68, v71, vcc
	v_mul_f32_e32 v68, 0x3f4ccccd, v68
	v_mul_f32_e32 v48, v48, v68
	v_mul_f32_e32 v49, v49, v68
	v_mul_f32_e32 v36, v36, v68
	v_mul_f32_e32 v37, v37, v68
	s_waitcnt vmcnt(3)
	v_pk_mul_f32 v[48:49], v[72:73], v[48:49]
	v_mul_f32_e32 v38, v38, v68
	v_mul_f32_e32 v39, v39, v68
	v_pk_mul_f32 v[32:33], v[48:49], v[32:33]
	v_mul_f32_e32 v48, v50, v68
	v_mul_f32_e32 v49, v51, v68
	v_cvt_pk_bf16_f32 v32, v32, v33
	v_pk_mul_f32 v[48:49], v[74:75], v[48:49]
	v_mul_f32_e32 v50, v54, v68
	v_mul_f32_e32 v51, v55, v68
	v_pk_mul_f32 v[34:35], v[48:49], v[34:35]
	v_mul_f32_e32 v48, v52, v68
	v_mul_f32_e32 v49, v53, v68
	v_cvt_pk_bf16_f32 v33, v34, v35
	global_store_dwordx2 v[82:83], v[32:33], off
	global_load_dwordx4 v[32:35], v65, s[62:63] offset:32
	s_waitcnt vmcnt(4)
	v_lshlrev_b32_e32 v52, 16, v76
	v_and_b32_e32 v53, 0xffff0000, v76
	v_lshlrev_b32_e32 v54, 16, v77
	v_and_b32_e32 v55, 0xffff0000, v77
	s_waitcnt vmcnt(0)
	v_pk_mul_f32 v[32:33], v[32:33], v[48:49]
	v_pk_mul_f32 v[34:35], v[34:35], v[50:51]
	v_pk_mul_f32 v[32:33], v[32:33], v[52:53]
	v_pk_mul_f32 v[34:35], v[34:35], v[54:55]
	v_cvt_pk_bf16_f32 v32, v32, v33
	v_cvt_pk_bf16_f32 v33, v34, v35
	global_store_dwordx2 v[82:83], v[32:33], off offset:16
	global_load_dwordx4 v[32:35], v65, s[62:63] offset:64
	v_mul_f32_e32 v48, v56, v68
	v_mul_f32_e32 v49, v57, v68
	v_mul_f32_e32 v50, v58, v68
	v_mul_f32_e32 v51, v59, v68
	v_lshlrev_b32_e32 v52, 16, v78
	v_and_b32_e32 v53, 0xffff0000, v78
	v_lshlrev_b32_e32 v54, 16, v79
	v_and_b32_e32 v55, 0xffff0000, v79
	v_lshlrev_b32_e32 v56, 16, v81
	v_and_b32_e32 v57, 0xffff0000, v81
	v_mul_f32_e32 v58, v96, v68
	v_mul_f32_e32 v59, v97, v68
	s_waitcnt vmcnt(0)
	v_pk_mul_f32 v[32:33], v[48:49], v[32:33]
	v_pk_mul_f32 v[34:35], v[50:51], v[34:35]
	v_pk_mul_f32 v[32:33], v[32:33], v[52:53]
	v_pk_mul_f32 v[34:35], v[34:35], v[54:55]
	v_cvt_pk_bf16_f32 v32, v32, v33
	v_cvt_pk_bf16_f32 v33, v34, v35
	global_store_dwordx2 v[82:83], v[32:33], off offset:32
	global_load_dwordx4 v[32:35], v65, s[62:63] offset:96
	s_nop 0
	global_load_dwordx2 v[48:49], v[66:67], off offset:64
	v_mul_f32_e32 v50, v60, v68
	v_mul_f32_e32 v51, v61, v68
	v_mul_f32_e32 v52, v62, v68
	v_mul_f32_e32 v53, v63, v68
	v_lshlrev_b32_e32 v54, 16, v80
	v_and_b32_e32 v55, 0xffff0000, v80
	s_waitcnt vmcnt(1)
	v_pk_mul_f32 v[32:33], v[50:51], v[32:33]
	v_pk_mul_f32 v[34:35], v[52:53], v[34:35]
	v_pk_mul_f32 v[32:33], v[32:33], v[54:55]
	v_pk_mul_f32 v[34:35], v[34:35], v[56:57]
	v_cvt_pk_bf16_f32 v32, v32, v33
	v_cvt_pk_bf16_f32 v33, v34, v35
	global_store_dwordx2 v[82:83], v[32:33], off offset:48
	global_load_dwordx4 v[32:35], v65, s[62:63] offset:128
	s_nop 0
	global_load_dwordx2 v[50:51], v[66:67], off offset:80
	global_load_dwordx2 v[52:53], v[66:67], off offset:96
	global_load_dwordx2 v[54:55], v[66:67], off offset:112
	v_mul_f32_e32 v56, v94, v68
	v_mul_f32_e32 v57, v95, v68
	s_waitcnt vmcnt(5)
	v_lshlrev_b32_e32 v60, 16, v48
	v_and_b32_e32 v61, 0xffff0000, v48
	v_lshlrev_b32_e32 v48, 16, v49
	v_and_b32_e32 v49, 0xffff0000, v49
	s_waitcnt vmcnt(3)
	v_pk_mul_f32 v[32:33], v[56:57], v[32:33]
	v_pk_mul_f32 v[34:35], v[58:59], v[34:35]
	v_pk_mul_f32 v[32:33], v[32:33], v[60:61]
	v_pk_mul_f32 v[34:35], v[34:35], v[48:49]
	v_cvt_pk_bf16_f32 v32, v32, v33
	v_cvt_pk_bf16_f32 v33, v34, v35
	global_store_dwordx2 v[82:83], v[32:33], off offset:64
	global_load_dwordx4 v[32:35], v65, s[62:63] offset:160
	s_waitcnt vmcnt(4)
	v_lshlrev_b32_e32 v48, 16, v50
	v_and_b32_e32 v49, 0xffff0000, v50
	v_lshlrev_b32_e32 v50, 16, v51
	v_and_b32_e32 v51, 0xffff0000, v51
	s_waitcnt vmcnt(0)
	v_pk_mul_f32 v[32:33], v[36:37], v[32:33]
	v_pk_mul_f32 v[34:35], v[38:39], v[34:35]
	v_pk_mul_f32 v[32:33], v[32:33], v[48:49]
	v_pk_mul_f32 v[34:35], v[34:35], v[50:51]
	v_cvt_pk_bf16_f32 v32, v32, v33
	v_cvt_pk_bf16_f32 v33, v34, v35
	global_store_dwordx2 v[82:83], v[32:33], off offset:80
	global_load_dwordx4 v[32:35], v65, s[62:63] offset:192
	v_mul_f32_e32 v36, v40, v68
	v_mul_f32_e32 v37, v41, v68
	v_mul_f32_e32 v38, v42, v68
	v_mul_f32_e32 v39, v43, v68
	v_lshlrev_b32_e32 v40, 16, v52
	v_and_b32_e32 v41, 0xffff0000, v52
	v_lshlrev_b32_e32 v42, 16, v53
	v_and_b32_e32 v43, 0xffff0000, v53
	s_waitcnt vmcnt(0)
	v_pk_mul_f32 v[32:33], v[36:37], v[32:33]
	v_pk_mul_f32 v[34:35], v[38:39], v[34:35]
	v_pk_mul_f32 v[32:33], v[32:33], v[40:41]
	v_pk_mul_f32 v[34:35], v[34:35], v[42:43]
	v_cvt_pk_bf16_f32 v32, v32, v33
	v_cvt_pk_bf16_f32 v33, v34, v35
	global_store_dwordx2 v[82:83], v[32:33], off offset:96
	global_load_dwordx4 v[32:35], v65, s[62:63] offset:224
	v_mul_f32_e32 v36, v44, v68
	v_mul_f32_e32 v37, v45, v68
	v_mul_f32_e32 v38, v46, v68
	v_mul_f32_e32 v39, v47, v68
	v_lshlrev_b32_e32 v40, 16, v54
	v_and_b32_e32 v41, 0xffff0000, v54
	v_lshlrev_b32_e32 v42, 16, v55
	v_and_b32_e32 v43, 0xffff0000, v55
	s_waitcnt vmcnt(0)
	v_pk_mul_f32 v[32:33], v[36:37], v[32:33]
	v_pk_mul_f32 v[34:35], v[38:39], v[34:35]
	v_pk_mul_f32 v[32:33], v[32:33], v[40:41]
	v_pk_mul_f32 v[34:35], v[34:35], v[42:43]
	v_cvt_pk_bf16_f32 v32, v32, v33
	v_cvt_pk_bf16_f32 v33, v34, v35
	global_store_dwordx2 v[82:83], v[32:33], off offset:112

; DI float xhalf(float v) { return __shfl_xor(v, 32); }
; template <int NKS>
; DI void attn_tile(const Params& p, int layer, int seq, int slot, int qt, char* smem, bool wr = true) {
;     ...
;     for (int qb = 0; qb < 2; ++qb) {
;       const float inv = 1.f / (lsum[qb] + xhalf(lsum[qb]));
;       if (sub == 1) {
; #pragma unroll
;         for (int eb = 0; eb < 2; ++eb)
; #pragma unroll
;           for (int i = 0; i < 16; ++i) xch[(qhalf * 32 + eb * 16 + i) * 64 + lane] = O[qb][eb][i] * inv;
;       }
;       __syncthreads();
;       if (sub == 0) {
;         float ss = 0.f;
; #pragma unroll
;         for (int eb = 0; eb < 2; ++eb)
; #pragma unroll
;           for (int i = 0; i < 16; ++i) {
;             float v = O[qb][eb][i] * inv - lam * xch[(qhalf * 32 + eb * 16 + i) * 64 + lane];
;             O[qb][eb][i] = v; ss += v * v;
;           }
;         ss += xhalf(ss);
;         const float rn = rsqrtf(ss * (1.f / 64.f) + EPS) * post;
.LBB0_686:
	s_andn2_b64 vcc, exec, s[8:9]
	s_waitcnt lgkmcnt(0)
	s_barrier
	s_cbranch_vccnz .LBB0_647
	ds_read2st64_b32 v[40:41], v69 offset1:1
	ds_read2st64_b32 v[36:37], v69 offset0:2 offset1:3
	ds_read2st64_b32 v[42:43], v69 offset0:4 offset1:5
	ds_read2st64_b32 v[44:45], v69 offset0:6 offset1:7
	ds_read2st64_b32 v[46:47], v69 offset0:8 offset1:9
	ds_read2st64_b32 v[48:49], v69 offset0:10 offset1:11
	ds_read2st64_b32 v[50:51], v69 offset0:12 offset1:13
	ds_read2st64_b32 v[52:53], v69 offset0:14 offset1:15
	ds_read2st64_b32 v[54:55], v69 offset0:24 offset1:25
	ds_read2st64_b32 v[56:57], v69 offset0:26 offset1:27
	ds_read2st64_b32 v[32:33], v69 offset0:28 offset1:29
	ds_read2st64_b32 v[38:39], v69 offset0:30 offset1:31
	ds_read2st64_b32 v[58:59], v69 offset0:16 offset1:17
	ds_read2st64_b32 v[60:61], v69 offset0:18 offset1:19
	ds_read2st64_b32 v[62:63], v69 offset0:20 offset1:21
	ds_read2st64_b32 v[66:67], v69 offset0:22 offset1:23
	s_waitcnt vmcnt(0) lgkmcnt(5)
	v_pk_mul_f32 v[32:33], v[64:65], v[32:33] op_sel_hi:[0,1]
	v_pk_fma_f32 v[12:13], v[12:13], v[34:35], v[32:33] op_sel_hi:[1,0,1] neg_lo:[0,0,1] neg_hi:[0,0,1]
	s_waitcnt lgkmcnt(4)
	v_pk_mul_f32 v[32:33], v[64:65], v[38:39] op_sel_hi:[0,1]
	v_pk_fma_f32 v[14:15], v[14:15], v[34:35], v[32:33] op_sel_hi:[1,0,1] neg_lo:[0,0,1] neg_hi:[0,0,1]
	v_lshl_add_u64 v[32:33], s[0:1], 0, v[160:161]
	v_lshl_add_u64 v[32:33], v[32:33], 0, v[128:129]
	v_pk_mul_f32 v[36:37], v[64:65], v[36:37] op_sel_hi:[0,1]
	global_load_dwordx2 v[72:73], v[32:33], off
	v_pk_fma_f32 v[18:19], v[18:19], v[34:35], v[36:37] op_sel_hi:[1,0,1] neg_lo:[0,0,1] neg_hi:[0,0,1]
	global_load_dwordx4 v[36:39], v65, s[62:63]
	v_pk_mul_f32 v[40:41], v[64:65], v[40:41] op_sel_hi:[0,1]
	v_pk_fma_f32 v[16:17], v[16:17], v[34:35], v[40:41] op_sel_hi:[1,0,1] neg_lo:[0,0,1] neg_hi:[0,0,1]
	v_pk_mul_f32 v[76:77], v[18:19], v[18:19]
	v_pk_mul_f32 v[40:41], v[16:17], v[16:17]
	v_pk_mul_f32 v[42:43], v[64:65], v[42:43] op_sel_hi:[0,1]
	v_add_f32_e32 v40, v40, v41
	v_pk_fma_f32 v[20:21], v[20:21], v[34:35], v[42:43] op_sel_hi:[1,0,1] neg_lo:[0,0,1] neg_hi:[0,0,1]
	v_add_f32_e32 v40, v40, v76
	v_pk_mul_f32 v[44:45], v[64:65], v[44:45] op_sel_hi:[0,1]
	v_pk_mul_f32 v[42:43], v[20:21], v[20:21]
	v_add_f32_e32 v40, v40, v77
	v_pk_fma_f32 v[22:23], v[22:23], v[34:35], v[44:45] op_sel_hi:[1,0,1] neg_lo:[0,0,1] neg_hi:[0,0,1]
	v_add_f32_e32 v40, v40, v42
	v_pk_mul_f32 v[44:45], v[22:23], v[22:23]
	v_pk_mul_f32 v[46:47], v[64:65], v[46:47] op_sel_hi:[0,1]
	v_add_f32_e32 v40, v40, v43
	v_pk_fma_f32 v[24:25], v[24:25], v[34:35], v[46:47] op_sel_hi:[1,0,1] neg_lo:[0,0,1] neg_hi:[0,0,1]
	v_add_f32_e32 v40, v40, v44
	v_pk_mul_f32 v[48:49], v[64:65], v[48:49] op_sel_hi:[0,1]
	v_pk_mul_f32 v[46:47], v[24:25], v[24:25]
	v_add_f32_e32 v40, v40, v45
	v_pk_fma_f32 v[26:27], v[26:27], v[34:35], v[48:49] op_sel_hi:[1,0,1] neg_lo:[0,0,1] neg_hi:[0,0,1]
	v_add_f32_e32 v40, v40, v46
	v_pk_mul_f32 v[48:49], v[26:27], v[26:27]
	v_pk_mul_f32 v[50:51], v[64:65], v[50:51] op_sel_hi:[0,1]
	v_add_f32_e32 v40, v40, v47
	v_pk_fma_f32 v[28:29], v[28:29], v[34:35], v[50:51] op_sel_hi:[1,0,1] neg_lo:[0,0,1] neg_hi:[0,0,1]
	v_add_f32_e32 v40, v40, v48
	v_pk_mul_f32 v[52:53], v[64:65], v[52:53] op_sel_hi:[0,1]
	v_pk_mul_f32 v[50:51], v[28:29], v[28:29]
	v_add_f32_e32 v40, v40, v49
	v_pk_fma_f32 v[30:31], v[30:31], v[34:35], v[52:53] op_sel_hi:[1,0,1] neg_lo:[0,0,1] neg_hi:[0,0,1]
	v_add_f32_e32 v40, v40, v50
	v_pk_mul_f32 v[52:53], v[30:31], v[30:31]
	s_waitcnt lgkmcnt(3)
	v_pk_mul_f32 v[58:59], v[64:65], v[58:59] op_sel_hi:[0,1]
	v_add_f32_e32 v40, v40, v51
	v_pk_fma_f32 v[58:59], v[0:1], v[34:35], v[58:59] op_sel_hi:[1,0,1] neg_lo:[0,0,1] neg_hi:[0,0,1]
	v_add_f32_e32 v40, v40, v52
	s_waitcnt lgkmcnt(2)
	v_pk_mul_f32 v[60:61], v[64:65], v[60:61] op_sel_hi:[0,1]
	v_pk_mul_f32 v[0:1], v[58:59], v[58:59]
	v_add_f32_e32 v40, v40, v53
	v_pk_fma_f32 v[60:61], v[2:3], v[34:35], v[60:61] op_sel_hi:[1,0,1] neg_lo:[0,0,1] neg_hi:[0,0,1]
	v_add_f32_e32 v0, v40, v0
	v_pk_mul_f32 v[2:3], v[60:61], v[60:61]
	s_waitcnt lgkmcnt(1)
	v_pk_mul_f32 v[62:63], v[64:65], v[62:63] op_sel_hi:[0,1]
	v_add_f32_e32 v0, v0, v1
	v_pk_fma_f32 v[4:5], v[4:5], v[34:35], v[62:63] op_sel_hi:[1,0,1] neg_lo:[0,0,1] neg_hi:[0,0,1]
	v_add_f32_e32 v0, v0, v2
	s_waitcnt lgkmcnt(0)
	v_pk_mul_f32 v[66:67], v[64:65], v[66:67] op_sel_hi:[0,1]
	v_pk_mul_f32 v[62:63], v[4:5], v[4:5]
	v_add_f32_e32 v0, v0, v3
	v_pk_fma_f32 v[6:7], v[6:7], v[34:35], v[66:67] op_sel_hi:[1,0,1] neg_lo:[0,0,1] neg_hi:[0,0,1]
	v_add_f32_e32 v0, v0, v62
	v_pk_mul_f32 v[66:67], v[6:7], v[6:7]
	v_pk_mul_f32 v[54:55], v[64:65], v[54:55] op_sel_hi:[0,1]
	v_add_f32_e32 v0, v0, v63
	v_pk_mul_f32 v[56:57], v[64:65], v[56:57] op_sel_hi:[0,1]
	v_pk_fma_f32 v[8:9], v[8:9], v[34:35], v[54:55] op_sel_hi:[1,0,1] neg_lo:[0,0,1] neg_hi:[0,0,1]
	v_add_f32_e32 v0, v0, v66
	v_pk_fma_f32 v[10:11], v[10:11], v[34:35], v[56:57] op_sel_hi:[1,0,1] neg_lo:[0,0,1] neg_hi:[0,0,1]
	v_pk_mul_f32 v[34:35], v[8:9], v[8:9]
	v_add_f32_e32 v0, v0, v67
	v_add_f32_e32 v0, v0, v34
	v_pk_mul_f32 v[56:57], v[10:11], v[10:11]
	v_add_f32_e32 v0, v0, v35
	v_add_f32_e32 v0, v0, v56
	v_pk_mul_f32 v[68:69], v[12:13], v[12:13]
	v_add_f32_e32 v0, v0, v57
	v_add_f32_e32 v0, v0, v68
	v_pk_mul_f32 v[70:71], v[14:15], v[14:15]
	v_add_f32_e32 v0, v0, v69
	v_add_f32_e32 v0, v0, v70
	v_add_f32_e32 v2, v0, v71
	ds_bpermute_b32 v3, v235, v2
	v_lshl_add_u64 v[74:75], s[16:17], 0, v[160:161]
	v_lshl_add_u64 v[44:45], v[74:75], 0, v[128:129]
	global_load_dwordx2 v[34:35], v[32:33], off offset:16
	global_load_dwordx2 v[40:41], v[32:33], off offset:32
	global_load_dwordx2 v[42:43], v[32:33], off offset:48
	s_waitcnt vmcnt(4)
; DI u32 pack2bf(float lo, float hi) { f32x2 v = {lo, hi}; return __builtin_bit_cast(u32, __builtin_convertvector(v, bf2_t)); }
; DI float bflo(u32 w) { return __uint_as_float(w << 16); }
; DI float bfhi(u32 w) { return __uint_as_float(w & 0xffff0000u); }
; DI float xhalf(float v) { return __shfl_xor(v, 32); }
; template <int NKS>
; DI void attn_tile(const Params& p, int layer, int seq, int slot, int qt, char* smem, bool wr = true) {
;     ...
;         ss += xhalf(ss);
;         const float rn = rsqrtf(ss * (1.f / 64.f) + EPS) * post;
;         const size_t t = (size_t)(q0 + 32 * qb + r);
; #pragma unroll
;         for (int eb = 0; eb < 2; ++eb)
; #pragma unroll
;           for (int g = 0; g < 4; ++g) {
;             int e = 32 * eb + 8 * g + 4 * h;
;             u32x2 gt = *(const u32x2*)(gate + t * 256 + e);
;             float4 nw = *(const float4*)(dnw + e);
;             u32x2 o = {pack2bf(O[qb][eb][4 * g] * rn * nw.x * bflo(gt[0]), O[qb][eb][4 * g + 1] * rn * nw.y * bfhi(gt[0])),
;                        pack2bf(O[qb][eb][4 * g + 2] * rn * nw.z * bflo(gt[1]), O[qb][eb][4 * g + 3] * rn * nw.w * bfhi(gt[1]))};
;             if (wr) *(u32x2*)(outb + t * 256 + e) = o;
;           }
	v_lshlrev_b32_e32 v0, 16, v72
	s_waitcnt lgkmcnt(0)
	v_add_f32_e32 v2, v2, v3
	v_fmamk_f32 v2, v2, 0x3c800000, v166
	v_mul_f32_e32 v3, 0x4b800000, v2
	v_cmp_gt_f32_e32 vcc, s27, v2
	v_and_b32_e32 v1, 0xffff0000, v72
	s_nop 0
	v_cndmask_b32_e32 v2, v2, v3, vcc
	v_rsq_f32_e32 v46, v2
	v_lshlrev_b32_e32 v2, 16, v73
	v_and_b32_e32 v3, 0xffff0000, v73
	v_mul_f32_e32 v47, 0x45800000, v46
	v_cndmask_b32_e32 v46, v46, v47, vcc
	v_mul_f32_e32 v46, 0x3f4ccccd, v46
	v_mul_f32_e32 v16, v16, v46
	v_mul_f32_e32 v17, v17, v46
	v_mul_f32_e32 v4, v4, v46
	v_mul_f32_e32 v5, v5, v46
	s_waitcnt vmcnt(3)
	v_pk_mul_f32 v[16:17], v[36:37], v[16:17]
	v_mul_f32_e32 v6, v6, v46
	v_mul_f32_e32 v7, v7, v46
	v_pk_mul_f32 v[0:1], v[16:17], v[0:1]
	v_mul_f32_e32 v16, v18, v46
	v_mul_f32_e32 v17, v19, v46
	v_cvt_pk_bf16_f32 v0, v0, v1
	v_pk_mul_f32 v[16:17], v[38:39], v[16:17]
	v_mul_f32_e32 v18, v22, v46
	v_mul_f32_e32 v19, v23, v46
	v_pk_mul_f32 v[2:3], v[16:17], v[2:3]
	v_mul_f32_e32 v16, v20, v46
	v_mul_f32_e32 v17, v21, v46
	v_cvt_pk_bf16_f32 v1, v2, v3
	global_store_dwordx2 v[44:45], v[0:1], off
	global_load_dwordx4 v[0:3], v65, s[62:63] offset:32
	s_waitcnt vmcnt(4)
	v_lshlrev_b32_e32 v20, 16, v34
	v_and_b32_e32 v21, 0xffff0000, v34
	v_lshlrev_b32_e32 v22, 16, v35
	v_and_b32_e32 v23, 0xffff0000, v35
	s_waitcnt vmcnt(0)
	v_pk_mul_f32 v[0:1], v[0:1], v[16:17]
	v_pk_mul_f32 v[2:3], v[2:3], v[18:19]
	v_pk_mul_f32 v[0:1], v[0:1], v[20:21]
	v_pk_mul_f32 v[2:3], v[2:3], v[22:23]
	v_cvt_pk_bf16_f32 v0, v0, v1
	v_cvt_pk_bf16_f32 v1, v2, v3
	global_store_dwordx2 v[44:45], v[0:1], off offset:16
	global_load_dwordx4 v[0:3], v65, s[62:63] offset:64
	v_mul_f32_e32 v16, v24, v46
	v_mul_f32_e32 v17, v25, v46
	v_mul_f32_e32 v18, v26, v46
	v_mul_f32_e32 v19, v27, v46
	v_lshlrev_b32_e32 v20, 16, v40
	v_and_b32_e32 v21, 0xffff0000, v40
	v_lshlrev_b32_e32 v22, 16, v41
	v_and_b32_e32 v23, 0xffff0000, v41
	v_lshlrev_b32_e32 v24, 16, v43
	v_and_b32_e32 v25, 0xffff0000, v43
	v_mul_f32_e32 v26, v60, v46
	v_mul_f32_e32 v27, v61, v46
	s_waitcnt vmcnt(0)
	v_pk_mul_f32 v[0:1], v[16:17], v[0:1]
	v_pk_mul_f32 v[2:3], v[18:19], v[2:3]
	v_pk_mul_f32 v[0:1], v[0:1], v[20:21]
	v_pk_mul_f32 v[2:3], v[2:3], v[22:23]
	v_cvt_pk_bf16_f32 v0, v0, v1
	v_cvt_pk_bf16_f32 v1, v2, v3
	global_store_dwordx2 v[44:45], v[0:1], off offset:32
	global_load_dwordx4 v[0:3], v65, s[62:63] offset:96
	s_nop 0
	global_load_dwordx2 v[16:17], v[32:33], off offset:64
	v_mul_f32_e32 v18, v28, v46
	v_mul_f32_e32 v19, v29, v46
	v_mul_f32_e32 v20, v30, v46
	v_mul_f32_e32 v21, v31, v46
	v_lshlrev_b32_e32 v22, 16, v42
	v_and_b32_e32 v23, 0xffff0000, v42
	s_waitcnt vmcnt(1)
	v_pk_mul_f32 v[0:1], v[18:19], v[0:1]
	v_pk_mul_f32 v[2:3], v[20:21], v[2:3]
	v_pk_mul_f32 v[0:1], v[0:1], v[22:23]
	v_pk_mul_f32 v[2:3], v[2:3], v[24:25]
	v_cvt_pk_bf16_f32 v0, v0, v1
	v_cvt_pk_bf16_f32 v1, v2, v3
	global_store_dwordx2 v[44:45], v[0:1], off offset:48
	global_load_dwordx4 v[0:3], v65, s[62:63] offset:128
	s_nop 0
	global_load_dwordx2 v[18:19], v[32:33], off offset:80
	global_load_dwordx2 v[20:21], v[32:33], off offset:96
	global_load_dwordx2 v[22:23], v[32:33], off offset:112
	v_mul_f32_e32 v24, v58, v46
	v_mul_f32_e32 v25, v59, v46
	s_waitcnt vmcnt(5)
	v_lshlrev_b32_e32 v28, 16, v16
	v_and_b32_e32 v29, 0xffff0000, v16
	v_lshlrev_b32_e32 v16, 16, v17
	v_and_b32_e32 v17, 0xffff0000, v17
	s_waitcnt vmcnt(3)
	v_pk_mul_f32 v[0:1], v[24:25], v[0:1]
	v_pk_mul_f32 v[2:3], v[26:27], v[2:3]
	v_pk_mul_f32 v[0:1], v[0:1], v[28:29]
	v_pk_mul_f32 v[2:3], v[2:3], v[16:17]
	v_cvt_pk_bf16_f32 v0, v0, v1
	v_cvt_pk_bf16_f32 v1, v2, v3
	global_store_dwordx2 v[44:45], v[0:1], off offset:64
	global_load_dwordx4 v[0:3], v65, s[62:63] offset:160
	s_waitcnt vmcnt(4)
	v_lshlrev_b32_e32 v16, 16, v18
	v_and_b32_e32 v17, 0xffff0000, v18
	v_lshlrev_b32_e32 v18, 16, v19
	v_and_b32_e32 v19, 0xffff0000, v19
	s_waitcnt vmcnt(0)
	v_pk_mul_f32 v[0:1], v[4:5], v[0:1]
	v_pk_mul_f32 v[2:3], v[6:7], v[2:3]
	v_pk_mul_f32 v[0:1], v[0:1], v[16:17]
	v_pk_mul_f32 v[2:3], v[2:3], v[18:19]
	v_cvt_pk_bf16_f32 v0, v0, v1
	v_cvt_pk_bf16_f32 v1, v2, v3
	global_store_dwordx2 v[44:45], v[0:1], off offset:80
	global_load_dwordx4 v[0:3], v65, s[62:63] offset:192
	v_mul_f32_e32 v4, v8, v46
	v_mul_f32_e32 v5, v9, v46
	v_mul_f32_e32 v6, v10, v46
	v_mul_f32_e32 v7, v11, v46
	v_lshlrev_b32_e32 v8, 16, v20
	v_and_b32_e32 v9, 0xffff0000, v20
	v_lshlrev_b32_e32 v10, 16, v21
	v_and_b32_e32 v11, 0xffff0000, v21
	s_waitcnt vmcnt(0)
	v_pk_mul_f32 v[0:1], v[4:5], v[0:1]
	v_pk_mul_f32 v[2:3], v[6:7], v[2:3]
	v_pk_mul_f32 v[0:1], v[0:1], v[8:9]
	v_pk_mul_f32 v[2:3], v[2:3], v[10:11]
	v_cvt_pk_bf16_f32 v0, v0, v1
	v_cvt_pk_bf16_f32 v1, v2, v3
	global_store_dwordx2 v[44:45], v[0:1], off offset:96
	global_load_dwordx4 v[0:3], v65, s[62:63] offset:224
	v_mul_f32_e32 v4, v12, v46
	v_mul_f32_e32 v5, v13, v46
	v_mul_f32_e32 v6, v14, v46
	v_mul_f32_e32 v7, v15, v46
	v_lshlrev_b32_e32 v8, 16, v22
	v_and_b32_e32 v9, 0xffff0000, v22
	v_lshlrev_b32_e32 v10, 16, v23
	v_and_b32_e32 v11, 0xffff0000, v23
	s_waitcnt vmcnt(0)
	v_pk_mul_f32 v[0:1], v[4:5], v[0:1]
	v_pk_mul_f32 v[2:3], v[6:7], v[2:3]
	v_pk_mul_f32 v[0:1], v[0:1], v[8:9]
	v_pk_mul_f32 v[2:3], v[2:3], v[10:11]
	v_cvt_pk_bf16_f32 v0, v0, v1
	v_cvt_pk_bf16_f32 v1, v2, v3
	global_store_dwordx2 v[44:45], v[0:1], off offset:112
	s_branch .LBB0_647

; DI u32 pack2bf(float lo, float hi) { f32x2 v = {lo, hi}; return __builtin_bit_cast(u32, __builtin_convertvector(v, bf2_t)); }
; DI float bflo(u32 w) { return __uint_as_float(w << 16); }
; DI float bfhi(u32 w) { return __uint_as_float(w & 0xffff0000u); }
; DI void hgrn_finalize(const Params& p, int layer) {
;     ...
;   for (int t = blockIdx.x * 4 + wave; t < T_TOK; t += gridDim.x * 4) {
;     size_t off = (size_t)t * 512 + lane * 8;
;     u32x4 a = *(const u32x4*)(of + off), b = *(const u32x4*)(ob + off), g = *(const u32x4*)(ga + off);
;     float v[8]; float ss = 0.f;
; #pragma unroll
;     for (int i = 0; i < 4; ++i) {
;       v[2 * i] = bflo(a[i]) + bflo(b[i]); v[2 * i + 1] = bfhi(a[i]) + bfhi(b[i]);
;       ss += v[2 * i] * v[2 * i] + v[2 * i + 1] * v[2 * i + 1];
;     }
;     ss += __shfl_xor(ss, 1); ss += __shfl_xor(ss, 2); ss += __shfl_xor(ss, 4); ss += __shfl_xor(ss, 8);
;     float rn = rsqrtf(ss * (1.f / 128.f) + EPS);
;     u32x4 o;
; #pragma unroll
;     for (int i = 0; i < 4; ++i)
;       o[i] = pack2bf(v[2 * i] * rn * wv[2 * i] * bflo(g[i]), v[2 * i + 1] * rn * wv[2 * i + 1] * bfhi(g[i]));
;     *(u32x4*)(of + off) = o;
;   }
.LBB0_704:
	v_ashrrev_i32_e32 v9, 31, v8
	v_lshlrev_b64 v[20:21], 10, v[8:9]
	v_lshl_or_b32 v20, v10, 1, v20
	v_lshl_add_u64 v[24:25], s[48:49], 0, v[20:21]
	v_lshl_add_u64 v[16:17], s[14:15], 0, v[20:21]
	global_load_dwordx4 v[12:15], v[24:25], off
	v_lshl_add_u64 v[20:21], s[12:13], 0, v[20:21]
	global_load_dwordx4 v[16:19], v[16:17], off
	v_add_u32_e32 v8, s6, v8
	global_load_dwordx4 v[20:23], v[20:21], off
	v_cmp_lt_i32_e32 vcc, s8, v8
	s_or_b64 s[4:5], vcc, s[4:5]
	s_waitcnt vmcnt(2)
	v_lshlrev_b32_e32 v26, 16, v15
	v_and_b32_e32 v27, 0xffff0000, v15
	s_waitcnt vmcnt(1)
	v_lshlrev_b32_e32 v28, 16, v19
	v_and_b32_e32 v29, 0xffff0000, v19
	v_lshlrev_b32_e32 v30, 16, v14
	v_and_b32_e32 v31, 0xffff0000, v14
	v_lshlrev_b32_e32 v14, 16, v18
	v_and_b32_e32 v15, 0xffff0000, v18
	v_lshlrev_b32_e32 v18, 16, v13
	v_and_b32_e32 v19, 0xffff0000, v13
	v_lshlrev_b32_e32 v32, 16, v17
	v_and_b32_e32 v33, 0xffff0000, v17
	v_lshlrev_b32_e32 v34, 16, v12
	v_and_b32_e32 v35, 0xffff0000, v12
	v_lshlrev_b32_e32 v12, 16, v16
	v_and_b32_e32 v13, 0xffff0000, v16
	v_pk_add_f32 v[16:17], v[26:27], v[28:29]
	v_pk_add_f32 v[14:15], v[30:31], v[14:15]
	v_pk_add_f32 v[18:19], v[18:19], v[32:33]
	v_pk_add_f32 v[12:13], v[34:35], v[12:13]
	v_mov_b32_e32 v26, v16
	v_mov_b32_e32 v27, v14
	v_mov_b32_e32 v30, v12
	v_mov_b32_e32 v31, v18
	v_mov_b32_e32 v28, v17
	v_mov_b32_e32 v29, v15
	v_mov_b32_e32 v32, v13
	v_mov_b32_e32 v33, v19
	v_pk_mul_f32 v[26:27], v[26:27], v[26:27]
	v_pk_mul_f32 v[30:31], v[30:31], v[30:31]
	v_pk_fma_f32 v[26:27], v[28:29], v[28:29], v[26:27]
	v_pk_fma_f32 v[28:29], v[32:33], v[32:33], v[30:31]
	s_waitcnt vmcnt(0)
	v_lshlrev_b32_e32 v30, 16, v20
	v_add_f32_e32 v9, v28, v29
	v_add_f32_e32 v9, v27, v9
	v_add_f32_e32 v9, v26, v9
	ds_bpermute_b32 v26, v240, v9
	v_lshlrev_b32_e32 v28, 16, v21
	v_and_b32_e32 v29, 0xffff0000, v21
	s_waitcnt lgkmcnt(0)
	v_add_f32_e32 v9, v9, v26
	ds_bpermute_b32 v26, v239, v9
	s_waitcnt lgkmcnt(0)
	v_add_f32_e32 v9, v9, v26
	ds_bpermute_b32 v27, v238, v9
	v_lshlrev_b32_e32 v26, 16, v22
	s_waitcnt lgkmcnt(0)
	v_add_f32_e32 v9, v9, v27
	ds_bpermute_b32 v31, v237, v9
	v_and_b32_e32 v27, 0xffff0000, v22
	s_waitcnt lgkmcnt(0)
	v_add_f32_e32 v9, v9, v31
	v_fmamk_f32 v9, v9, 0x3c000000, v11
	v_mul_f32_e32 v21, 0x4b800000, v9
	v_cmp_gt_f32_e64 s[0:1], s7, v9
	v_and_b32_e32 v31, 0xffff0000, v20
	v_lshlrev_b32_e32 v20, 16, v23
	v_cndmask_b32_e64 v9, v9, v21, s[0:1]
	v_rsq_f32_e32 v9, v9
	v_and_b32_e32 v21, 0xffff0000, v23
	v_mul_f32_e32 v22, 0x45800000, v9
	v_cndmask_b32_e64 v22, v9, v22, s[0:1]
	v_mul_f32_e32 v12, v12, v22
	v_mul_f32_e32 v13, v13, v22
	v_mul_f32_e32 v18, v18, v22
	v_mul_f32_e32 v19, v19, v22
	v_mul_f32_e32 v14, v14, v22
	v_mul_f32_e32 v15, v15, v22
	v_mul_f32_e32 v16, v16, v22
	v_mul_f32_e32 v17, v17, v22
	v_pk_mul_f32 v[12:13], v[4:5], v[12:13]
	v_pk_mul_f32 v[18:19], v[6:7], v[18:19]
	v_pk_mul_f32 v[14:15], v[0:1], v[14:15]
	v_pk_mul_f32 v[16:17], v[2:3], v[16:17]
	v_pk_mul_f32 v[12:13], v[12:13], v[30:31]
	v_pk_mul_f32 v[18:19], v[18:19], v[28:29]
	v_pk_mul_f32 v[14:15], v[14:15], v[26:27]
	v_pk_mul_f32 v[16:17], v[16:17], v[20:21]
	v_cvt_pk_bf16_f32 v12, v12, v13
	v_cvt_pk_bf16_f32 v13, v18, v19
	v_cvt_pk_bf16_f32 v14, v14, v15
	v_cvt_pk_bf16_f32 v15, v16, v17
	global_store_dwordx4 v[24:25], v[12:15], off
	s_andn2_b64 exec, exec, s[4:5]
	s_cbranch_execnz .LBB0_704

; template <bool IN_PROJ>
; DI void gemm_tile(const Params& p, int layer, int nt, int tt, char* smem) {
;     ...
; #pragma unroll
;   for (int ti = 0; ti < 2; ++ti) {
;     const int t = t0 + wt * 64 + ti * 32 + r;
;     const float rs = rstd[t];
; #pragma unroll
;     for (int fi = 0; fi < 4; ++fi)
; #pragma unroll
;       for (int i = 0; i < 16; ++i) acc[fi][ti][i] *= rs;
;     if (d.kind == K_SILU) {
.LBB0_834:
	s_xor_b64 s[8:9], s[2:3], -1
	s_xor_b64 s[4:5], s[4:5], -1
	s_lshl_b64 s[2:3], s[10:11], 2
	s_add_u32 s2, s66, s2
	s_addc_u32 s3, s67, s3
	s_ashr_i32 s1, s0, 31
	s_lshl_b64 s[0:1], s[0:1], 2
	s_add_u32 s0, s2, s0
	s_addc_u32 s1, s3, s1
	v_lshlrev_b32_e32 v192, 4, v201
	v_or_b32_e32 v96, s92, v200
	v_lshl_add_u64 v[194:195], s[0:1], 0, v[192:193]
	v_readlane_b32 s0, v249, 10
	v_ashrrev_i32_e32 v97, 31, v96
	v_readlane_b32 s1, v249, 11
	s_mov_b64 s[60:61], -1
	s_mov_b64 s[90:91], 0
	v_lshl_add_u64 v[196:197], v[96:97], 2, s[0:1]
	v_mov_b32_e32 v160, v204
	s_cmp_lt_i32 s13, 2
	s_mov_b64 s[10:11], 0
	s_mov_b64 s[0:1], 0
	s_mov_b64 s[2:3], 0
	s_waitcnt vmcnt(0)
	v_mul_f32_e32 v128, v64, v160
	v_mul_f32_e32 v129, v65, v160
	v_mul_f32_e32 v130, v66, v160
	v_mul_f32_e32 v131, v67, v160
	v_mul_f32_e32 v132, v68, v160
	v_mul_f32_e32 v133, v69, v160
	v_mul_f32_e32 v134, v70, v160
	v_mul_f32_e32 v135, v71, v160
	v_mul_f32_e32 v136, v72, v160
	v_mul_f32_e32 v137, v73, v160
	v_mul_f32_e32 v138, v74, v160
	v_mul_f32_e32 v139, v75, v160
	v_mul_f32_e32 v140, v76, v160
	v_mul_f32_e32 v141, v77, v160
	v_mul_f32_e32 v142, v78, v160
	v_mul_f32_e32 v143, v79, v160
	v_mul_f32_e32 v96, v80, v160
	v_mul_f32_e32 v97, v81, v160
	v_mul_f32_e32 v98, v82, v160
	v_mul_f32_e32 v99, v83, v160
	v_mul_f32_e32 v100, v84, v160
	v_mul_f32_e32 v101, v85, v160
	v_mul_f32_e32 v102, v86, v160
	v_mul_f32_e32 v103, v87, v160
	v_mul_f32_e32 v104, v88, v160
	v_mul_f32_e32 v105, v89, v160
	v_mul_f32_e32 v106, v90, v160
	v_mul_f32_e32 v107, v91, v160
	v_mul_f32_e32 v108, v92, v160
	v_mul_f32_e32 v109, v93, v160
	v_mul_f32_e32 v110, v94, v160
	v_mul_f32_e32 v111, v95, v160
	v_mul_f32_e32 v80, v112, v160
	v_mul_f32_e32 v81, v113, v160
	v_mul_f32_e32 v82, v114, v160
	v_mul_f32_e32 v83, v115, v160
	v_mul_f32_e32 v84, v116, v160
	v_mul_f32_e32 v85, v117, v160
	v_mul_f32_e32 v86, v118, v160
	v_mul_f32_e32 v87, v119, v160
	v_mul_f32_e32 v88, v120, v160
	v_mul_f32_e32 v89, v121, v160
	v_mul_f32_e32 v90, v122, v160
	v_mul_f32_e32 v91, v123, v160
	v_mul_f32_e32 v92, v124, v160
	v_mul_f32_e32 v93, v125, v160
	v_mul_f32_e32 v94, v126, v160
	v_mul_f32_e32 v95, v127, v160
	v_mul_f32_e32 v64, v144, v160
	v_mul_f32_e32 v65, v145, v160
	v_mul_f32_e32 v66, v146, v160
	v_mul_f32_e32 v67, v147, v160
	v_mul_f32_e32 v68, v148, v160
	v_mul_f32_e32 v69, v149, v160
	v_mul_f32_e32 v70, v150, v160
	v_mul_f32_e32 v71, v151, v160
	v_mul_f32_e32 v72, v152, v160
	v_mul_f32_e32 v73, v153, v160
	v_mul_f32_e32 v74, v154, v160
	v_mul_f32_e32 v75, v155, v160
	v_mul_f32_e32 v76, v156, v160
	v_mul_f32_e32 v77, v157, v160
	v_mul_f32_e32 v78, v158, v160
	v_mul_f32_e32 v79, v159, v160
	s_cbranch_scc1 .LBB0_846
	s_cmp_gt_i32 s13, 4
	s_cbranch_scc0 .LBB0_838
	s_mov_b64 s[2:3], -1
	s_mov_b64 s[60:61], 0
	s_cmp_eq_u32 s13, 5
	s_cbranch_scc0 .LBB0_838
	s_mov_b64 s[2:3], 0
	s_mov_b64 s[10:11], -1

; template <bool IN_PROJ>
; DI void gemm_tile(const Params& p, int layer, int nt, int tt, char* smem) {
;     ...
; #pragma unroll
;   for (int ti = 0; ti < 2; ++ti) {
;     const int t = t0 + wt * 64 + ti * 32 + r;
;     const float rs = rstd[t];
; #pragma unroll
;     for (int fi = 0; fi < 4; ++fi)
; #pragma unroll
;       for (int i = 0; i < 16; ++i) acc[fi][ti][i] *= rs;
;     if (d.kind == K_SILU) {
.LBB0_918:
	v_mov_b32_e32 v96, v205
	s_mov_b64 s[60:61], -1
	s_mov_b64 s[90:91], 0
	s_cmp_lt_i32 s13, 2
	s_mov_b64 s[10:11], 0
	s_mov_b64 s[0:1], 0
	s_mov_b64 s[2:3], 0
	s_waitcnt vmcnt(0)
	v_mul_f32_e32 v80, v0, v96
	v_mul_f32_e32 v81, v1, v96
	v_mul_f32_e32 v82, v2, v96
	v_mul_f32_e32 v83, v3, v96
	v_mul_f32_e32 v84, v4, v96
	v_mul_f32_e32 v85, v5, v96
	v_mul_f32_e32 v86, v6, v96
	v_mul_f32_e32 v87, v7, v96
	v_mul_f32_e32 v88, v8, v96
	v_mul_f32_e32 v89, v9, v96
	v_mul_f32_e32 v90, v10, v96
	v_mul_f32_e32 v91, v11, v96
	v_mul_f32_e32 v92, v12, v96
	v_mul_f32_e32 v93, v13, v96
	v_mul_f32_e32 v94, v14, v96
	v_mul_f32_e32 v95, v15, v96
	v_mul_f32_e32 v64, v16, v96
	v_mul_f32_e32 v65, v17, v96
	v_mul_f32_e32 v66, v18, v96
	v_mul_f32_e32 v67, v19, v96
	v_mul_f32_e32 v68, v20, v96
	v_mul_f32_e32 v69, v21, v96
	v_mul_f32_e32 v70, v22, v96
	v_mul_f32_e32 v71, v23, v96
	v_mul_f32_e32 v72, v24, v96
	v_mul_f32_e32 v73, v25, v96
	v_mul_f32_e32 v74, v26, v96
	v_mul_f32_e32 v75, v27, v96
	v_mul_f32_e32 v76, v28, v96
	v_mul_f32_e32 v77, v29, v96
	v_mul_f32_e32 v78, v30, v96
	v_mul_f32_e32 v79, v31, v96
	v_mul_f32_e32 v16, v32, v96
	v_mul_f32_e32 v17, v33, v96
	v_mul_f32_e32 v18, v34, v96
	v_mul_f32_e32 v19, v35, v96
	v_mul_f32_e32 v20, v36, v96
	v_mul_f32_e32 v21, v37, v96
	v_mul_f32_e32 v22, v38, v96
	v_mul_f32_e32 v23, v39, v96
	v_mul_f32_e32 v24, v40, v96
	v_mul_f32_e32 v25, v41, v96
	v_mul_f32_e32 v26, v42, v96
	v_mul_f32_e32 v27, v43, v96
	v_mul_f32_e32 v28, v44, v96
	v_mul_f32_e32 v29, v45, v96
	v_mul_f32_e32 v30, v46, v96
	v_mul_f32_e32 v31, v47, v96
	v_mul_f32_e32 v0, v48, v96
	v_mul_f32_e32 v1, v49, v96
	v_mul_f32_e32 v2, v50, v96
	v_mul_f32_e32 v3, v51, v96
	v_mul_f32_e32 v4, v52, v96
	v_mul_f32_e32 v5, v53, v96
	v_mul_f32_e32 v6, v54, v96
	v_mul_f32_e32 v7, v55, v96
	v_mul_f32_e32 v8, v56, v96
	v_mul_f32_e32 v9, v57, v96
	v_mul_f32_e32 v10, v58, v96
	v_mul_f32_e32 v11, v59, v96
	v_mul_f32_e32 v12, v60, v96
	v_mul_f32_e32 v13, v61, v96
	v_mul_f32_e32 v14, v62, v96
	v_mul_f32_e32 v15, v63, v96
	s_cbranch_scc1 .LBB0_934
	s_cmp_gt_i32 s13, 4
	s_cbranch_scc0 .LBB0_922
	s_mov_b64 s[2:3], -1
	s_mov_b64 s[60:61], 0
	s_cmp_eq_u32 s13, 5
	s_cbranch_scc0 .LBB0_922
	s_mov_b64 s[2:3], 0
	s_mov_b64 s[10:11], -1

; DI float xhalf(float v) { return __shfl_xor(v, 32); }
; template <int NKS>
; DI void attn_tile(const Params& p, int layer, int seq, int slot, int qt, char* smem, bool wr = true) {
;     ...
;     for (int qb = 0; qb < 2; ++qb) {
;       const float inv = 1.f / (lsum[qb] + xhalf(lsum[qb]));
;       if (sub == 1) {
; #pragma unroll
;         for (int eb = 0; eb < 2; ++eb)
; #pragma unroll
;           for (int i = 0; i < 16; ++i) xch[(qhalf * 32 + eb * 16 + i) * 64 + lane] = O[qb][eb][i] * inv;
;       }
;       __syncthreads();
;       if (sub == 0) {
;         float ss = 0.f;
; #pragma unroll
;         for (int eb = 0; eb < 2; ++eb)
; #pragma unroll
;           for (int i = 0; i < 16; ++i) {
;             float v = O[qb][eb][i] * inv - lam * xch[(qhalf * 32 + eb * 16 + i) * 64 + lane];
;             O[qb][eb][i] = v; ss += v * v;
;           }
;         ss += xhalf(ss);
;         const float rn = rsqrtf(ss * (1.f / 64.f) + EPS) * post;
.LBB0_1425:
	v_readlane_b32 s0, v249, 16
	v_readlane_b32 s1, v249, 17
	s_add_u32 s0, s0, s18
	s_addc_u32 s1, s1, s19
	s_cmp_lt_u32 s28, 2
	v_lshlrev_b32_e32 v65, 2, v169
	s_cselect_b64 s[8:9], -1, 0
	s_cmp_gt_u32 s28, 1
	v_lshlrev_b32_e32 v128, 1, v65
	v_lshlrev_b32_e32 v65, 2, v65
	v_lshl_or_b32 v69, s28, 13, v66
	s_waitcnt lgkmcnt(0)
	s_barrier
	s_cbranch_scc1 .LBB0_1427
	ds_read2st64_b32 v[76:77], v69 offset1:1
	ds_read2st64_b32 v[72:73], v69 offset0:2 offset1:3
	ds_read2st64_b32 v[78:79], v69 offset0:4 offset1:5
	ds_read2st64_b32 v[80:81], v69 offset0:6 offset1:7
	ds_read2st64_b32 v[82:83], v69 offset0:8 offset1:9
	ds_read2st64_b32 v[84:85], v69 offset0:10 offset1:11
	ds_read2st64_b32 v[86:87], v69 offset0:12 offset1:13
	ds_read2st64_b32 v[88:89], v69 offset0:14 offset1:15
	ds_read2st64_b32 v[90:91], v69 offset0:24 offset1:25
	ds_read2st64_b32 v[92:93], v69 offset0:26 offset1:27
	ds_read2st64_b32 v[66:67], v69 offset0:28 offset1:29
	ds_read2st64_b32 v[74:75], v69 offset0:30 offset1:31
	ds_read2st64_b32 v[94:95], v69 offset0:16 offset1:17
	ds_read2st64_b32 v[96:97], v69 offset0:18 offset1:19
	ds_read2st64_b32 v[98:99], v69 offset0:20 offset1:21
	ds_read2st64_b32 v[100:101], v69 offset0:22 offset1:23
	s_waitcnt vmcnt(0) lgkmcnt(5)
	v_pk_mul_f32 v[66:67], v[64:65], v[66:67] op_sel_hi:[0,1]
	v_pk_fma_f32 v[44:45], v[44:45], v[68:69], v[66:67] op_sel_hi:[1,0,1] neg_lo:[0,0,1] neg_hi:[0,0,1]
	s_waitcnt lgkmcnt(4)
	v_pk_mul_f32 v[66:67], v[64:65], v[74:75] op_sel_hi:[0,1]
	v_pk_fma_f32 v[46:47], v[46:47], v[68:69], v[66:67] op_sel_hi:[1,0,1] neg_lo:[0,0,1] neg_hi:[0,0,1]
	v_lshl_add_u64 v[66:67], s[0:1], 0, v[162:163]
	v_lshl_add_u64 v[66:67], v[66:67], 0, v[128:129]
	v_pk_mul_f32 v[72:73], v[64:65], v[72:73] op_sel_hi:[0,1]
	global_load_dwordx2 v[106:107], v[66:67], off
	v_pk_fma_f32 v[50:51], v[50:51], v[68:69], v[72:73] op_sel_hi:[1,0,1] neg_lo:[0,0,1] neg_hi:[0,0,1]
	global_load_dwordx4 v[72:75], v65, s[86:87] offset:256
	v_pk_mul_f32 v[76:77], v[64:65], v[76:77] op_sel_hi:[0,1]
	v_pk_fma_f32 v[48:49], v[48:49], v[68:69], v[76:77] op_sel_hi:[1,0,1] neg_lo:[0,0,1] neg_hi:[0,0,1]
	v_pk_mul_f32 v[80:81], v[64:65], v[80:81] op_sel_hi:[0,1]
	v_pk_mul_f32 v[76:77], v[48:49], v[48:49]
	v_pk_mul_f32 v[78:79], v[64:65], v[78:79] op_sel_hi:[0,1]
	v_pk_mul_f32 v[84:85], v[64:65], v[84:85] op_sel_hi:[0,1]
	v_pk_mul_f32 v[82:83], v[64:65], v[82:83] op_sel_hi:[0,1]
	v_pk_mul_f32 v[88:89], v[64:65], v[88:89] op_sel_hi:[0,1]
	v_pk_mul_f32 v[86:87], v[64:65], v[86:87] op_sel_hi:[0,1]
	s_waitcnt lgkmcnt(2)
	v_pk_mul_f32 v[96:97], v[64:65], v[96:97] op_sel_hi:[0,1]
	v_pk_mul_f32 v[94:95], v[64:65], v[94:95] op_sel_hi:[0,1]
	s_waitcnt lgkmcnt(0)
	v_pk_mul_f32 v[100:101], v[64:65], v[100:101] op_sel_hi:[0,1]
	v_pk_mul_f32 v[98:99], v[64:65], v[98:99] op_sel_hi:[0,1]
	v_pk_mul_f32 v[92:93], v[64:65], v[92:93] op_sel_hi:[0,1]
	v_pk_mul_f32 v[90:91], v[64:65], v[90:91] op_sel_hi:[0,1]
	v_pk_mul_f32 v[110:111], v[50:51], v[50:51]
	v_pk_fma_f32 v[54:55], v[54:55], v[68:69], v[80:81] op_sel_hi:[1,0,1] neg_lo:[0,0,1] neg_hi:[0,0,1]
	v_pk_fma_f32 v[52:53], v[52:53], v[68:69], v[78:79] op_sel_hi:[1,0,1] neg_lo:[0,0,1] neg_hi:[0,0,1]
	v_pk_fma_f32 v[58:59], v[58:59], v[68:69], v[84:85] op_sel_hi:[1,0,1] neg_lo:[0,0,1] neg_hi:[0,0,1]
	v_pk_fma_f32 v[56:57], v[56:57], v[68:69], v[82:83] op_sel_hi:[1,0,1] neg_lo:[0,0,1] neg_hi:[0,0,1]
	v_pk_fma_f32 v[62:63], v[62:63], v[68:69], v[88:89] op_sel_hi:[1,0,1] neg_lo:[0,0,1] neg_hi:[0,0,1]
	v_pk_fma_f32 v[60:61], v[60:61], v[68:69], v[86:87] op_sel_hi:[1,0,1] neg_lo:[0,0,1] neg_hi:[0,0,1]
	v_pk_fma_f32 v[96:97], v[34:35], v[68:69], v[96:97] op_sel_hi:[1,0,1] neg_lo:[0,0,1] neg_hi:[0,0,1]
	v_pk_fma_f32 v[94:95], v[32:33], v[68:69], v[94:95] op_sel_hi:[1,0,1] neg_lo:[0,0,1] neg_hi:[0,0,1]
	v_pk_fma_f32 v[38:39], v[38:39], v[68:69], v[100:101] op_sel_hi:[1,0,1] neg_lo:[0,0,1] neg_hi:[0,0,1]
	v_pk_fma_f32 v[36:37], v[36:37], v[68:69], v[98:99] op_sel_hi:[1,0,1] neg_lo:[0,0,1] neg_hi:[0,0,1]
	v_pk_fma_f32 v[42:43], v[42:43], v[68:69], v[92:93] op_sel_hi:[1,0,1] neg_lo:[0,0,1] neg_hi:[0,0,1]
	v_pk_fma_f32 v[40:41], v[40:41], v[68:69], v[90:91] op_sel_hi:[1,0,1] neg_lo:[0,0,1] neg_hi:[0,0,1]
	v_add_f32_e32 v68, v76, v77
	v_add_f32_e32 v68, v68, v110
	v_pk_mul_f32 v[78:79], v[52:53], v[52:53]
	v_add_f32_e32 v68, v68, v111
	v_add_f32_e32 v68, v68, v78
	v_pk_mul_f32 v[80:81], v[54:55], v[54:55]
	v_add_f32_e32 v68, v68, v79
	v_add_f32_e32 v68, v68, v80
	v_pk_mul_f32 v[82:83], v[56:57], v[56:57]
	v_add_f32_e32 v68, v68, v81
	v_add_f32_e32 v68, v68, v82
	v_pk_mul_f32 v[84:85], v[58:59], v[58:59]
	v_add_f32_e32 v68, v68, v83
	v_add_f32_e32 v68, v68, v84
	v_pk_mul_f32 v[86:87], v[60:61], v[60:61]
	v_add_f32_e32 v68, v68, v85
	v_add_f32_e32 v68, v68, v86
	v_pk_mul_f32 v[88:89], v[62:63], v[62:63]
	v_add_f32_e32 v68, v68, v87
	v_add_f32_e32 v68, v68, v88
	v_pk_mul_f32 v[32:33], v[94:95], v[94:95]
	v_add_f32_e32 v68, v68, v89
	v_add_f32_e32 v32, v68, v32
	v_pk_mul_f32 v[34:35], v[96:97], v[96:97]
	v_add_f32_e32 v32, v32, v33
	v_add_f32_e32 v32, v32, v34
	v_pk_mul_f32 v[98:99], v[36:37], v[36:37]
	v_add_f32_e32 v32, v32, v35
	v_add_f32_e32 v32, v32, v98
	v_pk_mul_f32 v[100:101], v[38:39], v[38:39]
	v_add_f32_e32 v32, v32, v99
	v_add_f32_e32 v32, v32, v100
	v_pk_mul_f32 v[90:91], v[40:41], v[40:41]
	v_add_f32_e32 v32, v32, v101
	v_add_f32_e32 v32, v32, v90
	v_pk_mul_f32 v[92:93], v[42:43], v[42:43]
	v_add_f32_e32 v32, v32, v91
	v_add_f32_e32 v32, v32, v92
	v_pk_mul_f32 v[102:103], v[44:45], v[44:45]
	v_add_f32_e32 v32, v32, v93
	v_add_f32_e32 v32, v32, v102
	v_pk_mul_f32 v[104:105], v[46:47], v[46:47]
	v_add_f32_e32 v32, v32, v103
	v_add_f32_e32 v32, v32, v104
	v_add_f32_e32 v34, v32, v105
	ds_bpermute_b32 v35, v235, v34
	v_lshl_add_u64 v[108:109], s[16:17], 0, v[162:163]
	v_lshl_add_u64 v[82:83], v[108:109], 0, v[128:129]
	global_load_dwordx2 v[76:77], v[66:67], off offset:16
	global_load_dwordx2 v[78:79], v[66:67], off offset:32
	global_load_dwordx2 v[80:81], v[66:67], off offset:48
	s_waitcnt vmcnt(4)
; DI u32 pack2bf(float lo, float hi) { f32x2 v = {lo, hi}; return __builtin_bit_cast(u32, __builtin_convertvector(v, bf2_t)); }
; DI float bflo(u32 w) { return __uint_as_float(w << 16); }
; DI float bfhi(u32 w) { return __uint_as_float(w & 0xffff0000u); }
; DI float xhalf(float v) { return __shfl_xor(v, 32); }
; template <int NKS>
; DI void attn_tile(const Params& p, int layer, int seq, int slot, int qt, char* smem, bool wr = true) {
;     ...
;         ss += xhalf(ss);
;         const float rn = rsqrtf(ss * (1.f / 64.f) + EPS) * post;
;         const size_t t = (size_t)(q0 + 32 * qb + r);
; #pragma unroll
;         for (int eb = 0; eb < 2; ++eb)
; #pragma unroll
;           for (int g = 0; g < 4; ++g) {
;             int e = 32 * eb + 8 * g + 4 * h;
;             u32x2 gt = *(const u32x2*)(gate + t * 256 + e);
;             float4 nw = *(const float4*)(dnw + e);
;             u32x2 o = {pack2bf(O[qb][eb][4 * g] * rn * nw.x * bflo(gt[0]), O[qb][eb][4 * g + 1] * rn * nw.y * bfhi(gt[0])),
;                        pack2bf(O[qb][eb][4 * g + 2] * rn * nw.z * bflo(gt[1]), O[qb][eb][4 * g + 3] * rn * nw.w * bfhi(gt[1]))};
;             if (wr) *(u32x2*)(outb + t * 256 + e) = o;
;           }
	v_lshlrev_b32_e32 v32, 16, v106
	s_waitcnt lgkmcnt(0)
	v_add_f32_e32 v34, v34, v35
	v_fmamk_f32 v34, v34, 0x3c800000, v167
	v_mul_f32_e32 v35, 0x4b800000, v34
	v_cmp_gt_f32_e32 vcc, s27, v34
	v_and_b32_e32 v33, 0xffff0000, v106
	s_nop 0
	v_cndmask_b32_e32 v34, v34, v35, vcc
	v_rsq_f32_e32 v68, v34
	v_lshlrev_b32_e32 v34, 16, v107
	v_and_b32_e32 v35, 0xffff0000, v107
	v_mul_f32_e32 v71, 0x45800000, v68
	v_cndmask_b32_e32 v68, v68, v71, vcc
	v_mul_f32_e32 v68, v164, v68
	v_mul_f32_e32 v48, v48, v68
	v_mul_f32_e32 v49, v49, v68
	v_mul_f32_e32 v36, v36, v68
	v_mul_f32_e32 v37, v37, v68
	s_waitcnt vmcnt(3)
	v_pk_mul_f32 v[48:49], v[72:73], v[48:49]
	v_mul_f32_e32 v38, v38, v68
	v_mul_f32_e32 v39, v39, v68
	v_pk_mul_f32 v[32:33], v[48:49], v[32:33]
	v_mul_f32_e32 v48, v50, v68
	v_mul_f32_e32 v49, v51, v68
	v_cvt_pk_bf16_f32 v32, v32, v33
	v_pk_mul_f32 v[48:49], v[74:75], v[48:49]
	v_mul_f32_e32 v50, v54, v68
	v_mul_f32_e32 v51, v55, v68
	v_pk_mul_f32 v[34:35], v[48:49], v[34:35]
	v_mul_f32_e32 v48, v52, v68
	v_mul_f32_e32 v49, v53, v68
	v_cvt_pk_bf16_f32 v33, v34, v35
	global_store_dwordx2 v[82:83], v[32:33], off
	global_load_dwordx4 v[32:35], v65, s[86:87] offset:288
	s_waitcnt vmcnt(4)
	v_lshlrev_b32_e32 v52, 16, v76
	v_and_b32_e32 v53, 0xffff0000, v76
	v_lshlrev_b32_e32 v54, 16, v77
	v_and_b32_e32 v55, 0xffff0000, v77
	s_waitcnt vmcnt(0)
	v_pk_mul_f32 v[32:33], v[32:33], v[48:49]
	v_pk_mul_f32 v[34:35], v[34:35], v[50:51]
	v_pk_mul_f32 v[32:33], v[32:33], v[52:53]
	v_pk_mul_f32 v[34:35], v[34:35], v[54:55]
	v_cvt_pk_bf16_f32 v32, v32, v33
	v_cvt_pk_bf16_f32 v33, v34, v35
	global_store_dwordx2 v[82:83], v[32:33], off offset:16
	global_load_dwordx4 v[32:35], v65, s[86:87] offset:320
	v_mul_f32_e32 v48, v56, v68
	v_mul_f32_e32 v49, v57, v68
	v_mul_f32_e32 v50, v58, v68
	v_mul_f32_e32 v51, v59, v68
	v_lshlrev_b32_e32 v52, 16, v78
	v_and_b32_e32 v53, 0xffff0000, v78
	v_lshlrev_b32_e32 v54, 16, v79
	v_and_b32_e32 v55, 0xffff0000, v79
	v_lshlrev_b32_e32 v56, 16, v81
	v_and_b32_e32 v57, 0xffff0000, v81
	v_mul_f32_e32 v58, v96, v68
	v_mul_f32_e32 v59, v97, v68
	s_waitcnt vmcnt(0)
	v_pk_mul_f32 v[32:33], v[48:49], v[32:33]
	v_pk_mul_f32 v[34:35], v[50:51], v[34:35]
	v_pk_mul_f32 v[32:33], v[32:33], v[52:53]
	v_pk_mul_f32 v[34:35], v[34:35], v[54:55]
	v_cvt_pk_bf16_f32 v32, v32, v33
	v_cvt_pk_bf16_f32 v33, v34, v35
	global_store_dwordx2 v[82:83], v[32:33], off offset:32
	global_load_dwordx4 v[32:35], v65, s[86:87] offset:352
	s_nop 0
	global_load_dwordx2 v[48:49], v[66:67], off offset:64
	v_mul_f32_e32 v50, v60, v68
	v_mul_f32_e32 v51, v61, v68
	v_mul_f32_e32 v52, v62, v68
	v_mul_f32_e32 v53, v63, v68
	v_lshlrev_b32_e32 v54, 16, v80
	v_and_b32_e32 v55, 0xffff0000, v80
	s_waitcnt vmcnt(1)
	v_pk_mul_f32 v[32:33], v[50:51], v[32:33]
	v_pk_mul_f32 v[34:35], v[52:53], v[34:35]
	v_pk_mul_f32 v[32:33], v[32:33], v[54:55]
	v_pk_mul_f32 v[34:35], v[34:35], v[56:57]
	v_cvt_pk_bf16_f32 v32, v32, v33
	v_cvt_pk_bf16_f32 v33, v34, v35
	global_store_dwordx2 v[82:83], v[32:33], off offset:48
	global_load_dwordx4 v[32:35], v65, s[86:87] offset:384
	s_nop 0
	global_load_dwordx2 v[50:51], v[66:67], off offset:80
	global_load_dwordx2 v[52:53], v[66:67], off offset:96
	global_load_dwordx2 v[54:55], v[66:67], off offset:112
	v_mul_f32_e32 v56, v94, v68
	v_mul_f32_e32 v57, v95, v68
	s_waitcnt vmcnt(5)
	v_lshlrev_b32_e32 v60, 16, v48
	v_and_b32_e32 v61, 0xffff0000, v48
	v_lshlrev_b32_e32 v48, 16, v49
	v_and_b32_e32 v49, 0xffff0000, v49
	s_waitcnt vmcnt(3)
	v_pk_mul_f32 v[32:33], v[56:57], v[32:33]
	v_pk_mul_f32 v[34:35], v[58:59], v[34:35]
	v_pk_mul_f32 v[32:33], v[32:33], v[60:61]
	v_pk_mul_f32 v[34:35], v[34:35], v[48:49]
	v_cvt_pk_bf16_f32 v32, v32, v33
	v_cvt_pk_bf16_f32 v33, v34, v35
	global_store_dwordx2 v[82:83], v[32:33], off offset:64
	global_load_dwordx4 v[32:35], v65, s[86:87] offset:416
	s_waitcnt vmcnt(4)
	v_lshlrev_b32_e32 v48, 16, v50
	v_and_b32_e32 v49, 0xffff0000, v50
	v_lshlrev_b32_e32 v50, 16, v51
	v_and_b32_e32 v51, 0xffff0000, v51
	s_waitcnt vmcnt(0)
	v_pk_mul_f32 v[32:33], v[36:37], v[32:33]
	v_pk_mul_f32 v[34:35], v[38:39], v[34:35]
	v_pk_mul_f32 v[32:33], v[32:33], v[48:49]
	v_pk_mul_f32 v[34:35], v[34:35], v[50:51]
	v_cvt_pk_bf16_f32 v32, v32, v33
	v_cvt_pk_bf16_f32 v33, v34, v35
	global_store_dwordx2 v[82:83], v[32:33], off offset:80
	global_load_dwordx4 v[32:35], v65, s[86:87] offset:448
	v_mul_f32_e32 v36, v40, v68
	v_mul_f32_e32 v37, v41, v68
	v_mul_f32_e32 v38, v42, v68
	v_mul_f32_e32 v39, v43, v68
	v_lshlrev_b32_e32 v40, 16, v52
	v_and_b32_e32 v41, 0xffff0000, v52
	v_lshlrev_b32_e32 v42, 16, v53
	v_and_b32_e32 v43, 0xffff0000, v53
	s_waitcnt vmcnt(0)
	v_pk_mul_f32 v[32:33], v[36:37], v[32:33]
	v_pk_mul_f32 v[34:35], v[38:39], v[34:35]
	v_pk_mul_f32 v[32:33], v[32:33], v[40:41]
	v_pk_mul_f32 v[34:35], v[34:35], v[42:43]
	v_cvt_pk_bf16_f32 v32, v32, v33
	v_cvt_pk_bf16_f32 v33, v34, v35
	global_store_dwordx2 v[82:83], v[32:33], off offset:96
	global_load_dwordx4 v[32:35], v65, s[86:87] offset:480
	v_mul_f32_e32 v36, v44, v68
	v_mul_f32_e32 v37, v45, v68
	v_mul_f32_e32 v38, v46, v68
	v_mul_f32_e32 v39, v47, v68
	v_lshlrev_b32_e32 v40, 16, v54
	v_and_b32_e32 v41, 0xffff0000, v54
	v_lshlrev_b32_e32 v42, 16, v55
	v_and_b32_e32 v43, 0xffff0000, v55
	s_waitcnt vmcnt(0)
	v_pk_mul_f32 v[32:33], v[36:37], v[32:33]
	v_pk_mul_f32 v[34:35], v[38:39], v[34:35]
	v_pk_mul_f32 v[32:33], v[32:33], v[40:41]
	v_pk_mul_f32 v[34:35], v[34:35], v[42:43]
	v_cvt_pk_bf16_f32 v32, v32, v33
	v_cvt_pk_bf16_f32 v33, v34, v35
	global_store_dwordx2 v[82:83], v[32:33], off offset:112

; DI float xhalf(float v) { return __shfl_xor(v, 32); }
; template <int NKS>
; DI void attn_tile(const Params& p, int layer, int seq, int slot, int qt, char* smem, bool wr = true) {
;     ...
;     for (int qb = 0; qb < 2; ++qb) {
;       const float inv = 1.f / (lsum[qb] + xhalf(lsum[qb]));
;       if (sub == 1) {
; #pragma unroll
;         for (int eb = 0; eb < 2; ++eb)
; #pragma unroll
;           for (int i = 0; i < 16; ++i) xch[(qhalf * 32 + eb * 16 + i) * 64 + lane] = O[qb][eb][i] * inv;
;       }
;       __syncthreads();
;       if (sub == 0) {
;         float ss = 0.f;
; #pragma unroll
;         for (int eb = 0; eb < 2; ++eb)
; #pragma unroll
;           for (int i = 0; i < 16; ++i) {
;             float v = O[qb][eb][i] * inv - lam * xch[(qhalf * 32 + eb * 16 + i) * 64 + lane];
;             O[qb][eb][i] = v; ss += v * v;
;           }
;         ss += xhalf(ss);
;         const float rn = rsqrtf(ss * (1.f / 64.f) + EPS) * post;
.LBB0_1429:
	s_andn2_b64 vcc, exec, s[8:9]
	s_waitcnt lgkmcnt(0)
	s_barrier
	s_cbranch_vccnz .LBB0_1390
	ds_read2st64_b32 v[40:41], v69 offset1:1
	ds_read2st64_b32 v[36:37], v69 offset0:2 offset1:3
	ds_read2st64_b32 v[42:43], v69 offset0:4 offset1:5
	ds_read2st64_b32 v[44:45], v69 offset0:6 offset1:7
	ds_read2st64_b32 v[46:47], v69 offset0:8 offset1:9
	ds_read2st64_b32 v[48:49], v69 offset0:10 offset1:11
	ds_read2st64_b32 v[50:51], v69 offset0:12 offset1:13
	ds_read2st64_b32 v[52:53], v69 offset0:14 offset1:15
	ds_read2st64_b32 v[54:55], v69 offset0:24 offset1:25
	ds_read2st64_b32 v[56:57], v69 offset0:26 offset1:27
	ds_read2st64_b32 v[32:33], v69 offset0:28 offset1:29
	ds_read2st64_b32 v[38:39], v69 offset0:30 offset1:31
	ds_read2st64_b32 v[58:59], v69 offset0:16 offset1:17
	ds_read2st64_b32 v[60:61], v69 offset0:18 offset1:19
	ds_read2st64_b32 v[62:63], v69 offset0:20 offset1:21
	ds_read2st64_b32 v[66:67], v69 offset0:22 offset1:23
	s_waitcnt vmcnt(0) lgkmcnt(5)
	v_pk_mul_f32 v[32:33], v[64:65], v[32:33] op_sel_hi:[0,1]
	v_pk_fma_f32 v[12:13], v[12:13], v[34:35], v[32:33] op_sel_hi:[1,0,1] neg_lo:[0,0,1] neg_hi:[0,0,1]
	s_waitcnt lgkmcnt(4)
	v_pk_mul_f32 v[32:33], v[64:65], v[38:39] op_sel_hi:[0,1]
	v_pk_fma_f32 v[14:15], v[14:15], v[34:35], v[32:33] op_sel_hi:[1,0,1] neg_lo:[0,0,1] neg_hi:[0,0,1]
	v_lshl_add_u64 v[32:33], s[0:1], 0, v[160:161]
	v_lshl_add_u64 v[32:33], v[32:33], 0, v[128:129]
	v_pk_mul_f32 v[36:37], v[64:65], v[36:37] op_sel_hi:[0,1]
	global_load_dwordx2 v[72:73], v[32:33], off
	v_pk_fma_f32 v[18:19], v[18:19], v[34:35], v[36:37] op_sel_hi:[1,0,1] neg_lo:[0,0,1] neg_hi:[0,0,1]
	global_load_dwordx4 v[36:39], v65, s[86:87] offset:256
	v_pk_mul_f32 v[40:41], v[64:65], v[40:41] op_sel_hi:[0,1]
	v_pk_fma_f32 v[16:17], v[16:17], v[34:35], v[40:41] op_sel_hi:[1,0,1] neg_lo:[0,0,1] neg_hi:[0,0,1]
	v_pk_mul_f32 v[76:77], v[18:19], v[18:19]
	v_pk_mul_f32 v[40:41], v[16:17], v[16:17]
	v_pk_mul_f32 v[42:43], v[64:65], v[42:43] op_sel_hi:[0,1]
	v_add_f32_e32 v40, v40, v41
	v_pk_fma_f32 v[20:21], v[20:21], v[34:35], v[42:43] op_sel_hi:[1,0,1] neg_lo:[0,0,1] neg_hi:[0,0,1]
	v_add_f32_e32 v40, v40, v76
	v_pk_mul_f32 v[44:45], v[64:65], v[44:45] op_sel_hi:[0,1]
	v_pk_mul_f32 v[42:43], v[20:21], v[20:21]
	v_add_f32_e32 v40, v40, v77
	v_pk_fma_f32 v[22:23], v[22:23], v[34:35], v[44:45] op_sel_hi:[1,0,1] neg_lo:[0,0,1] neg_hi:[0,0,1]
	v_add_f32_e32 v40, v40, v42
	v_pk_mul_f32 v[44:45], v[22:23], v[22:23]
	v_pk_mul_f32 v[46:47], v[64:65], v[46:47] op_sel_hi:[0,1]
	v_add_f32_e32 v40, v40, v43
	v_pk_fma_f32 v[24:25], v[24:25], v[34:35], v[46:47] op_sel_hi:[1,0,1] neg_lo:[0,0,1] neg_hi:[0,0,1]
	v_add_f32_e32 v40, v40, v44
	v_pk_mul_f32 v[48:49], v[64:65], v[48:49] op_sel_hi:[0,1]
	v_pk_mul_f32 v[46:47], v[24:25], v[24:25]
	v_add_f32_e32 v40, v40, v45
	v_pk_fma_f32 v[26:27], v[26:27], v[34:35], v[48:49] op_sel_hi:[1,0,1] neg_lo:[0,0,1] neg_hi:[0,0,1]
	v_add_f32_e32 v40, v40, v46
	v_pk_mul_f32 v[48:49], v[26:27], v[26:27]
	v_pk_mul_f32 v[50:51], v[64:65], v[50:51] op_sel_hi:[0,1]
	v_add_f32_e32 v40, v40, v47
	v_pk_fma_f32 v[28:29], v[28:29], v[34:35], v[50:51] op_sel_hi:[1,0,1] neg_lo:[0,0,1] neg_hi:[0,0,1]
	v_add_f32_e32 v40, v40, v48
	v_pk_mul_f32 v[52:53], v[64:65], v[52:53] op_sel_hi:[0,1]
	v_pk_mul_f32 v[50:51], v[28:29], v[28:29]
	v_add_f32_e32 v40, v40, v49
	v_pk_fma_f32 v[30:31], v[30:31], v[34:35], v[52:53] op_sel_hi:[1,0,1] neg_lo:[0,0,1] neg_hi:[0,0,1]
	v_add_f32_e32 v40, v40, v50
	v_pk_mul_f32 v[52:53], v[30:31], v[30:31]
	s_waitcnt lgkmcnt(3)
	v_pk_mul_f32 v[58:59], v[64:65], v[58:59] op_sel_hi:[0,1]
	v_add_f32_e32 v40, v40, v51
	v_pk_fma_f32 v[58:59], v[0:1], v[34:35], v[58:59] op_sel_hi:[1,0,1] neg_lo:[0,0,1] neg_hi:[0,0,1]
	v_add_f32_e32 v40, v40, v52
	s_waitcnt lgkmcnt(2)
	v_pk_mul_f32 v[60:61], v[64:65], v[60:61] op_sel_hi:[0,1]
	v_pk_mul_f32 v[0:1], v[58:59], v[58:59]
	v_add_f32_e32 v40, v40, v53
	v_pk_fma_f32 v[60:61], v[2:3], v[34:35], v[60:61] op_sel_hi:[1,0,1] neg_lo:[0,0,1] neg_hi:[0,0,1]
	v_add_f32_e32 v0, v40, v0
	v_pk_mul_f32 v[2:3], v[60:61], v[60:61]
	s_waitcnt lgkmcnt(1)
	v_pk_mul_f32 v[62:63], v[64:65], v[62:63] op_sel_hi:[0,1]
	v_add_f32_e32 v0, v0, v1
	v_pk_fma_f32 v[4:5], v[4:5], v[34:35], v[62:63] op_sel_hi:[1,0,1] neg_lo:[0,0,1] neg_hi:[0,0,1]
	v_add_f32_e32 v0, v0, v2
	s_waitcnt lgkmcnt(0)
	v_pk_mul_f32 v[66:67], v[64:65], v[66:67] op_sel_hi:[0,1]
	v_pk_mul_f32 v[62:63], v[4:5], v[4:5]
	v_add_f32_e32 v0, v0, v3
	v_pk_fma_f32 v[6:7], v[6:7], v[34:35], v[66:67] op_sel_hi:[1,0,1] neg_lo:[0,0,1] neg_hi:[0,0,1]
	v_add_f32_e32 v0, v0, v62
	v_pk_mul_f32 v[66:67], v[6:7], v[6:7]
	v_pk_mul_f32 v[54:55], v[64:65], v[54:55] op_sel_hi:[0,1]
	v_add_f32_e32 v0, v0, v63
	v_pk_mul_f32 v[56:57], v[64:65], v[56:57] op_sel_hi:[0,1]
	v_pk_fma_f32 v[8:9], v[8:9], v[34:35], v[54:55] op_sel_hi:[1,0,1] neg_lo:[0,0,1] neg_hi:[0,0,1]
	v_add_f32_e32 v0, v0, v66
	v_pk_fma_f32 v[10:11], v[10:11], v[34:35], v[56:57] op_sel_hi:[1,0,1] neg_lo:[0,0,1] neg_hi:[0,0,1]
	v_pk_mul_f32 v[34:35], v[8:9], v[8:9]
	v_add_f32_e32 v0, v0, v67
	v_add_f32_e32 v0, v0, v34
	v_pk_mul_f32 v[56:57], v[10:11], v[10:11]
	v_add_f32_e32 v0, v0, v35
	v_add_f32_e32 v0, v0, v56
	v_pk_mul_f32 v[68:69], v[12:13], v[12:13]
	v_add_f32_e32 v0, v0, v57
	v_add_f32_e32 v0, v0, v68
	v_pk_mul_f32 v[70:71], v[14:15], v[14:15]
	v_add_f32_e32 v0, v0, v69
	v_add_f32_e32 v0, v0, v70
	v_add_f32_e32 v2, v0, v71
	ds_bpermute_b32 v3, v235, v2
	v_lshl_add_u64 v[74:75], s[16:17], 0, v[160:161]
	v_lshl_add_u64 v[44:45], v[74:75], 0, v[128:129]
	global_load_dwordx2 v[34:35], v[32:33], off offset:16
	global_load_dwordx2 v[40:41], v[32:33], off offset:32
	global_load_dwordx2 v[42:43], v[32:33], off offset:48
	s_waitcnt vmcnt(4)
; DI u32 pack2bf(float lo, float hi) { f32x2 v = {lo, hi}; return __builtin_bit_cast(u32, __builtin_convertvector(v, bf2_t)); }
; DI float bflo(u32 w) { return __uint_as_float(w << 16); }
; DI float bfhi(u32 w) { return __uint_as_float(w & 0xffff0000u); }
; DI float xhalf(float v) { return __shfl_xor(v, 32); }
; template <int NKS>
; DI void attn_tile(const Params& p, int layer, int seq, int slot, int qt, char* smem, bool wr = true) {
;     ...
;         ss += xhalf(ss);
;         const float rn = rsqrtf(ss * (1.f / 64.f) + EPS) * post;
;         const size_t t = (size_t)(q0 + 32 * qb + r);
; #pragma unroll
;         for (int eb = 0; eb < 2; ++eb)
; #pragma unroll
;           for (int g = 0; g < 4; ++g) {
;             int e = 32 * eb + 8 * g + 4 * h;
;             u32x2 gt = *(const u32x2*)(gate + t * 256 + e);
;             float4 nw = *(const float4*)(dnw + e);
;             u32x2 o = {pack2bf(O[qb][eb][4 * g] * rn * nw.x * bflo(gt[0]), O[qb][eb][4 * g + 1] * rn * nw.y * bfhi(gt[0])),
;                        pack2bf(O[qb][eb][4 * g + 2] * rn * nw.z * bflo(gt[1]), O[qb][eb][4 * g + 3] * rn * nw.w * bfhi(gt[1]))};
;             if (wr) *(u32x2*)(outb + t * 256 + e) = o;
;           }
	v_lshlrev_b32_e32 v0, 16, v72
	s_waitcnt lgkmcnt(0)
	v_add_f32_e32 v2, v2, v3
	v_fmamk_f32 v2, v2, 0x3c800000, v167
	v_mul_f32_e32 v3, 0x4b800000, v2
	v_cmp_gt_f32_e32 vcc, s27, v2
	v_and_b32_e32 v1, 0xffff0000, v72
	s_nop 0
	v_cndmask_b32_e32 v2, v2, v3, vcc
	v_rsq_f32_e32 v46, v2
	v_lshlrev_b32_e32 v2, 16, v73
	v_and_b32_e32 v3, 0xffff0000, v73
	v_mul_f32_e32 v47, 0x45800000, v46
	v_cndmask_b32_e32 v46, v46, v47, vcc
	v_mul_f32_e32 v46, v164, v46
	v_mul_f32_e32 v16, v16, v46
	v_mul_f32_e32 v17, v17, v46
	v_mul_f32_e32 v4, v4, v46
	v_mul_f32_e32 v5, v5, v46
	s_waitcnt vmcnt(3)
	v_pk_mul_f32 v[16:17], v[36:37], v[16:17]
	v_mul_f32_e32 v6, v6, v46
	v_mul_f32_e32 v7, v7, v46
	v_pk_mul_f32 v[0:1], v[16:17], v[0:1]
	v_mul_f32_e32 v16, v18, v46
	v_mul_f32_e32 v17, v19, v46
	v_cvt_pk_bf16_f32 v0, v0, v1
	v_pk_mul_f32 v[16:17], v[38:39], v[16:17]
	v_mul_f32_e32 v18, v22, v46
	v_mul_f32_e32 v19, v23, v46
	v_pk_mul_f32 v[2:3], v[16:17], v[2:3]
	v_mul_f32_e32 v16, v20, v46
	v_mul_f32_e32 v17, v21, v46
	v_cvt_pk_bf16_f32 v1, v2, v3
	global_store_dwordx2 v[44:45], v[0:1], off
	global_load_dwordx4 v[0:3], v65, s[86:87] offset:288
	s_waitcnt vmcnt(4)
	v_lshlrev_b32_e32 v20, 16, v34
	v_and_b32_e32 v21, 0xffff0000, v34
	v_lshlrev_b32_e32 v22, 16, v35
	v_and_b32_e32 v23, 0xffff0000, v35
	s_waitcnt vmcnt(0)
	v_pk_mul_f32 v[0:1], v[0:1], v[16:17]
	v_pk_mul_f32 v[2:3], v[2:3], v[18:19]
	v_pk_mul_f32 v[0:1], v[0:1], v[20:21]
	v_pk_mul_f32 v[2:3], v[2:3], v[22:23]
	v_cvt_pk_bf16_f32 v0, v0, v1
	v_cvt_pk_bf16_f32 v1, v2, v3
	global_store_dwordx2 v[44:45], v[0:1], off offset:16
	global_load_dwordx4 v[0:3], v65, s[86:87] offset:320
	v_mul_f32_e32 v16, v24, v46
	v_mul_f32_e32 v17, v25, v46
	v_mul_f32_e32 v18, v26, v46
	v_mul_f32_e32 v19, v27, v46
	v_lshlrev_b32_e32 v20, 16, v40
	v_and_b32_e32 v21, 0xffff0000, v40
	v_lshlrev_b32_e32 v22, 16, v41
	v_and_b32_e32 v23, 0xffff0000, v41
	v_lshlrev_b32_e32 v24, 16, v43
	v_and_b32_e32 v25, 0xffff0000, v43
	v_mul_f32_e32 v26, v60, v46
	v_mul_f32_e32 v27, v61, v46
	s_waitcnt vmcnt(0)
	v_pk_mul_f32 v[0:1], v[16:17], v[0:1]
	v_pk_mul_f32 v[2:3], v[18:19], v[2:3]
	v_pk_mul_f32 v[0:1], v[0:1], v[20:21]
	v_pk_mul_f32 v[2:3], v[2:3], v[22:23]
	v_cvt_pk_bf16_f32 v0, v0, v1
	v_cvt_pk_bf16_f32 v1, v2, v3
	global_store_dwordx2 v[44:45], v[0:1], off offset:32
	global_load_dwordx4 v[0:3], v65, s[86:87] offset:352
	s_nop 0
	global_load_dwordx2 v[16:17], v[32:33], off offset:64
	v_mul_f32_e32 v18, v28, v46
	v_mul_f32_e32 v19, v29, v46
	v_mul_f32_e32 v20, v30, v46
	v_mul_f32_e32 v21, v31, v46
	v_lshlrev_b32_e32 v22, 16, v42
	v_and_b32_e32 v23, 0xffff0000, v42
	s_waitcnt vmcnt(1)
	v_pk_mul_f32 v[0:1], v[18:19], v[0:1]
	v_pk_mul_f32 v[2:3], v[20:21], v[2:3]
	v_pk_mul_f32 v[0:1], v[0:1], v[22:23]
	v_pk_mul_f32 v[2:3], v[2:3], v[24:25]
	v_cvt_pk_bf16_f32 v0, v0, v1
	v_cvt_pk_bf16_f32 v1, v2, v3
	global_store_dwordx2 v[44:45], v[0:1], off offset:48
	global_load_dwordx4 v[0:3], v65, s[86:87] offset:384
	s_nop 0
	global_load_dwordx2 v[18:19], v[32:33], off offset:80
	global_load_dwordx2 v[20:21], v[32:33], off offset:96
	global_load_dwordx2 v[22:23], v[32:33], off offset:112
	v_mul_f32_e32 v24, v58, v46
	v_mul_f32_e32 v25, v59, v46
	s_waitcnt vmcnt(5)
	v_lshlrev_b32_e32 v28, 16, v16
	v_and_b32_e32 v29, 0xffff0000, v16
	v_lshlrev_b32_e32 v16, 16, v17
	v_and_b32_e32 v17, 0xffff0000, v17
	s_waitcnt vmcnt(3)
	v_pk_mul_f32 v[0:1], v[24:25], v[0:1]
	v_pk_mul_f32 v[2:3], v[26:27], v[2:3]
	v_pk_mul_f32 v[0:1], v[0:1], v[28:29]
	v_pk_mul_f32 v[2:3], v[2:3], v[16:17]
	v_cvt_pk_bf16_f32 v0, v0, v1
	v_cvt_pk_bf16_f32 v1, v2, v3
	global_store_dwordx2 v[44:45], v[0:1], off offset:64
	global_load_dwordx4 v[0:3], v65, s[86:87] offset:416
	s_waitcnt vmcnt(4)
	v_lshlrev_b32_e32 v16, 16, v18
	v_and_b32_e32 v17, 0xffff0000, v18
	v_lshlrev_b32_e32 v18, 16, v19
	v_and_b32_e32 v19, 0xffff0000, v19
	s_waitcnt vmcnt(0)
	v_pk_mul_f32 v[0:1], v[4:5], v[0:1]
	v_pk_mul_f32 v[2:3], v[6:7], v[2:3]
	v_pk_mul_f32 v[0:1], v[0:1], v[16:17]
	v_pk_mul_f32 v[2:3], v[2:3], v[18:19]
	v_cvt_pk_bf16_f32 v0, v0, v1
	v_cvt_pk_bf16_f32 v1, v2, v3
	global_store_dwordx2 v[44:45], v[0:1], off offset:80
	global_load_dwordx4 v[0:3], v65, s[86:87] offset:448
	v_mul_f32_e32 v4, v8, v46
	v_mul_f32_e32 v5, v9, v46
	v_mul_f32_e32 v6, v10, v46
	v_mul_f32_e32 v7, v11, v46
	v_lshlrev_b32_e32 v8, 16, v20
	v_and_b32_e32 v9, 0xffff0000, v20
	v_lshlrev_b32_e32 v10, 16, v21
	v_and_b32_e32 v11, 0xffff0000, v21
	s_waitcnt vmcnt(0)
	v_pk_mul_f32 v[0:1], v[4:5], v[0:1]
	v_pk_mul_f32 v[2:3], v[6:7], v[2:3]
	v_pk_mul_f32 v[0:1], v[0:1], v[8:9]
	v_pk_mul_f32 v[2:3], v[2:3], v[10:11]
	v_cvt_pk_bf16_f32 v0, v0, v1
	v_cvt_pk_bf16_f32 v1, v2, v3
	global_store_dwordx2 v[44:45], v[0:1], off offset:96
	global_load_dwordx4 v[0:3], v65, s[86:87] offset:480
	v_mul_f32_e32 v4, v12, v46
	v_mul_f32_e32 v5, v13, v46
	v_mul_f32_e32 v6, v14, v46
	v_mul_f32_e32 v7, v15, v46
	v_lshlrev_b32_e32 v8, 16, v22
	v_and_b32_e32 v9, 0xffff0000, v22
	v_lshlrev_b32_e32 v10, 16, v23
	v_and_b32_e32 v11, 0xffff0000, v23
	s_waitcnt vmcnt(0)
	v_pk_mul_f32 v[0:1], v[4:5], v[0:1]
	v_pk_mul_f32 v[2:3], v[6:7], v[2:3]
	v_pk_mul_f32 v[0:1], v[0:1], v[8:9]
	v_pk_mul_f32 v[2:3], v[2:3], v[10:11]
	v_cvt_pk_bf16_f32 v0, v0, v1
	v_cvt_pk_bf16_f32 v1, v2, v3
	global_store_dwordx2 v[44:45], v[0:1], off offset:112
	s_branch .LBB0_1390
